# adds: residual-GEMM per-tile gate/scale/gain loads no longer waited at the tile header (arithmetic deferred to the epilogue); in-proj and V^T tile headers drop the compiler's vmcnt(0) before the K-loo
# speedup vs baseline: 1.0057x; 1.0057x over previous
;     __device__ __forceinline__ Pre prefetch(const Unit& u, int tid) const { return prenorm_load(stats, u.pn * BM, sW + (size_t)(u.pn >> 4) * SW_ROWS + u.pm * BM, tid); }
;     __device__ __forceinline__ Pre prefetch(const Unit& u, int tid) const { return prenorm_load(stats, u.pm * BM, sW + (size_t)(u.pm >> 4) * SW_ROWS + u.pn * BM, tid); }
;     __device__ __forceinline__ Pre prefetch(const Unit& u, int tid) const { return prenorm_load(stats, u.pm * BM, sW + (size_t)(u.pm >> 4) * SW_ROWS + u.pn * BM, tid); }
; #define PG8_STAGE(bufoff, gbase, voff) do { _Pragma("unroll") for (int _i = 0; _i < 2; ++_i) \
;         __builtin_amdgcn_global_load_lds((const unsigned*)((const char*)(gbase) + (voff)[_i]), (LAS unsigned*)(lds + (bufoff) + ldsw + _i * 8192), 16, 0, 0); } while (0)
; #define PG8_LDA(dst, b, h) do { _Pragma("unroll") for (int m = 0; m < 4; ++m) _Pragma("unroll") for (int k = 0; k < 2; ++k) dst[m][k] = *(const LAS bf16x8*)(lds + PG8_SA(b, h) + aoff + m * 2048 + k * 1024); } while (0)
; #define PG8_LDB(dst, b, h) do { _Pragma("unroll") for (int n = 0; n < 2; ++n) _Pragma("unroll") for (int k = 0; k < 2; ++k) dst[n][k] = *(const LAS bf16x8*)(lds + PG8_SB(b, h) + boff + n * 2048 + k * 1024); } while (0)
; #define PG8_WAIT_V(n) asm volatile("s_waitcnt vmcnt(" #n ")" ::: "memory")
; template <class Epi, class Sched>
; __device__ __forceinline__ void gemm_phase(LAS unsigned char* lds, const Gemm g, const Sched& S, const Epi& E, const int tid) {
;     ...
;     for (;;) {
;         const bool has_next = S.next(ui + 1, nxt);
;         const char* nA = has_next ? (const char*)g.A + (size_t)nxt.pm * tstep : cA; const char* nB = has_next ? (const char*)g.Bt + (size_t)nxt.pn * tstep : cB;
;         const typename Epi::Pre pre = E.prefetch(cur, tid);
;         for (int t = 0; t < nt; t += 2) {
;             const bool last = (t == nt - 2);
;             const char* a1 = cA + (size_t)(t + 1) * kstep;
;             const char* a2 = last ? nA : cA + (size_t)(t + 2) * kstep; const char* b2 = last ? nB : cB + (size_t)(t + 2) * kstep;
;             const char* a3 = a2 + kstep; const char* b3 = b2 + kstep;
;             PG8_LDB(B0, 0, 0); PG8_LDB(B1, 0, 1); PG8_SCHED; PG8_LDA(At, 0, 0); PG8_STAGE(PG8_SA(1, 1), a1 + hstep, voffA);
;             PG8_WAIT_V(8); PG8_WAIT_L(0); PG8_BAR; PG8_MMA(0, 0, At, B0); PG8_MMA(0, 1, At, B1); PG8_BAR; PG8_SCHED;
.LBB0_265:
	s_or_b64 exec, exec, s[38:39]
	s_ashr_i32 s23, s22, 31
	s_lshl_b64 s[38:39], s[22:23], 19
	s_add_u32 s38, s46, s38
	s_addc_u32 s39, s47, s39
	s_and_b64 s[56:57], s[4:5], exec
	s_cselect_b32 s23, s39, s7
	s_cselect_b32 s56, s38, s6
	s_ashr_i32 s55, s54, 31
	s_lshl_b64 s[58:59], s[54:55], 19
	s_add_u32 s62, s35, s58
	s_addc_u32 s63, s84, s59
	s_and_b64 s[58:59], s[4:5], exec
	s_cselect_b32 s55, s63, s65
	s_cselect_b32 s57, s62, s64
	s_add_u32 s6, s6, 0x40080
	s_addc_u32 s7, s7, 0
	s_add_u32 s58, s64, 0x100
	s_addc_u32 s59, s65, 0
	s_mov_b32 s60, -2
	s_add_u32 s61, s6, 0xfffc0080
	s_addc_u32 s64, s7, -1
	s_add_i32 s70, 0, 0x10000
	s_cmp_eq_u32 s60, 12
	s_cselect_b32 s67, s23, s64
	s_cselect_b32 s66, s56, s61
	v_add_u32_e32 v81, s70, v216
	s_cselect_b32 s65, s55, s59
	s_cselect_b32 s64, s57, s58
	s_add_i32 s61, 0, 0x14000
	ds_read_b128 v[88:91], v81
	ds_read_b128 v[92:95], v81 offset:1024
	ds_read_b128 v[144:147], v81 offset:2048
	ds_read_b128 v[148:151], v81 offset:3072
	v_add_u32_e32 v81, s61, v216
	ds_read_b128 v[152:155], v81
	ds_read_b128 v[156:159], v81 offset:1024
	ds_read_b128 v[178:181], v81 offset:2048
	ds_read_b128 v[182:185], v81 offset:3072
	v_lshl_add_u64 v[82:83], s[6:7], 0, v[174:175]
	s_add_i32 m0, s73, 0xc000
	ds_read_b128 v[186:189], v230
	ds_read_b128 v[198:201], v230 offset:1024
	ds_read_b128 v[202:205], v230 offset:2048
	ds_read_b128 v[206:209], v230 offset:3072
	ds_read_b128 v[234:237], v230 offset:4096
	ds_read_b128 v[238:241], v230 offset:5120
	ds_read_b128 v[242:245], v230 offset:6144
	ds_read_b128 v[246:249], v230 offset:7168
	global_load_lds_dwordx4 v[82:83], off
	v_lshl_add_u64 v[82:83], s[6:7], 0, v[176:177]
	s_add_i32 m0, s73, 0xe000
	s_nop 0
	global_load_lds_dwordx4 v[82:83], off
	s_waitcnt vmcnt(8)
	s_waitcnt lgkmcnt(0)
	s_barrier
	s_setprio 1
	s_waitcnt lgkmcnt(0)
	v_mfma_f32_16x16x32_bf16 v[140:143], v[88:91], v[186:189], 0
	v_mfma_f32_16x16x32_bf16 v[136:139], v[144:147], v[186:189], 0
	v_mfma_f32_16x16x32_bf16 v[124:127], v[88:91], v[202:205], 0
	v_mfma_f32_16x16x32_bf16 v[120:123], v[144:147], v[202:205], 0
	v_mfma_f32_16x16x32_bf16 v[108:111], v[88:91], v[234:237], 0
	v_mfma_f32_16x16x32_bf16 v[104:107], v[144:147], v[234:237], 0
	v_mfma_f32_16x16x32_bf16 v[82:85], v[88:91], v[242:245], 0
	v_mfma_f32_16x16x32_bf16 v[76:79], v[144:147], v[242:245], 0
	v_mfma_f32_16x16x32_bf16 v[140:143], v[92:95], v[198:201], v[140:143]
	v_mfma_f32_16x16x32_bf16 v[136:139], v[148:151], v[198:201], v[136:139]
	v_mfma_f32_16x16x32_bf16 v[124:127], v[92:95], v[206:209], v[124:127]
	v_mfma_f32_16x16x32_bf16 v[120:123], v[148:151], v[206:209], v[120:123]
	v_mfma_f32_16x16x32_bf16 v[108:111], v[92:95], v[238:241], v[108:111]
	v_mfma_f32_16x16x32_bf16 v[104:107], v[148:151], v[238:241], v[104:107]
	v_mfma_f32_16x16x32_bf16 v[82:85], v[92:95], v[246:249], v[82:85]
	v_mfma_f32_16x16x32_bf16 v[76:79], v[148:151], v[246:249], v[76:79]
	s_setprio 0
	s_setprio 1
	v_mfma_f32_16x16x32_bf16 v[132:135], v[152:155], v[186:189], 0
	v_mfma_f32_16x16x32_bf16 v[128:131], v[178:181], v[186:189], 0
	v_mfma_f32_16x16x32_bf16 v[116:119], v[152:155], v[202:205], 0
	v_mfma_f32_16x16x32_bf16 v[112:115], v[178:181], v[202:205], 0
	v_mfma_f32_16x16x32_bf16 v[100:103], v[152:155], v[234:237], 0
	v_mfma_f32_16x16x32_bf16 v[96:99], v[178:181], v[234:237], 0
	v_mfma_f32_16x16x32_bf16 v[68:71], v[152:155], v[242:245], 0
	v_mfma_f32_16x16x32_bf16 v[64:67], v[178:181], v[242:245], 0
	v_mfma_f32_16x16x32_bf16 v[132:135], v[156:159], v[198:201], v[132:135]
	v_mfma_f32_16x16x32_bf16 v[128:131], v[182:185], v[198:201], v[128:131]
	v_mfma_f32_16x16x32_bf16 v[116:119], v[156:159], v[206:209], v[116:119]
	v_mfma_f32_16x16x32_bf16 v[112:115], v[182:185], v[206:209], v[112:115]
	v_mfma_f32_16x16x32_bf16 v[100:103], v[156:159], v[238:241], v[100:103]
	v_mfma_f32_16x16x32_bf16 v[96:99], v[182:185], v[238:241], v[96:99]
	v_mfma_f32_16x16x32_bf16 v[68:71], v[156:159], v[246:249], v[68:71]
	v_mfma_f32_16x16x32_bf16 v[64:67], v[182:185], v[246:249], v[64:67]
	s_setprio 0
	s_barrier
	s_add_i32 s70, s70, s12
	v_lshl_add_u64 v[190:191], s[64:65], 0, v[164:165]
	s_mov_b32 m0, s70
	ds_read_b128 v[186:189], v230 offset:16384
	ds_read_b128 v[198:201], v230 offset:17408
	ds_read_b128 v[202:205], v230 offset:18432
	ds_read_b128 v[206:209], v230 offset:19456
	ds_read_b128 v[234:237], v230 offset:20480
	ds_read_b128 v[238:241], v230 offset:21504
	ds_read_b128 v[242:245], v230 offset:22528
	ds_read_b128 v[246:249], v230 offset:23552
	global_load_lds_dwordx4 v[190:191], off
	s_add_i32 m0, s70, 0x2000
	s_add_u32 s70, s64, 0x40000
	v_lshl_add_u64 v[250:251], s[64:65], 0, v[168:169]
	s_addc_u32 s71, s65, 0
	s_add_i32 s61, s61, s12
	global_load_lds_dwordx4 v[250:251], off
	v_lshl_add_u64 v[86:87], s[70:71], 0, v[164:165]
	s_mov_b32 m0, s61
	v_lshl_add_u64 v[224:225], s[66:67], 0, v[162:163]
	global_load_lds_dwordx4 v[86:87], off
	v_lshl_add_u64 v[86:87], s[70:71], 0, v[168:169]
	s_add_i32 m0, s61, 0x2000
	v_lshl_add_u64 v[226:227], s[66:67], 0, v[166:167]
	global_load_lds_dwordx4 v[86:87], off
	s_mov_b32 m0, s73
	s_nop 0
	global_load_lds_dwordx4 v[224:225], off
	s_mov_b32 m0, s74
	s_nop 0
	global_load_lds_dwordx4 v[226:227], off
	s_waitcnt vmcnt(8)
	s_waitcnt lgkmcnt(0)
	s_barrier
; #define PG8_STAGE(bufoff, gbase, voff) do { _Pragma("unroll") for (int _i = 0; _i < 2; ++_i) \
;         __builtin_amdgcn_global_load_lds((const unsigned*)((const char*)(gbase) + (voff)[_i]), (LAS unsigned*)(lds + (bufoff) + ldsw + _i * 8192), 16, 0, 0); } while (0)
; #define PG8_LDA(dst, b, h) do { _Pragma("unroll") for (int m = 0; m < 4; ++m) _Pragma("unroll") for (int k = 0; k < 2; ++k) dst[m][k] = *(const LAS bf16x8*)(lds + PG8_SA(b, h) + aoff + m * 2048 + k * 1024); } while (0)
; #define PG8_LDB(dst, b, h) do { _Pragma("unroll") for (int n = 0; n < 2; ++n) _Pragma("unroll") for (int k = 0; k < 2; ++k) dst[n][k] = *(const LAS bf16x8*)(lds + PG8_SB(b, h) + boff + n * 2048 + k * 1024); } while (0)
; #define PG8_MMA(ai, bj, At, Bt) do { __builtin_amdgcn_s_setprio(1); _Pragma("unroll") for (int m = 0; m < 4; ++m) _Pragma("unroll") for (int n = 0; n < 2; ++n) _Pragma("unroll") for (int k = 0; k < 2; ++k) \
;         acc[ai][bj][m][n] = __builtin_amdgcn_mfma_f32_16x16x32_bf16(Bt[n][k], At[m][k], acc[ai][bj][m][n], 0, 0, 0); __builtin_amdgcn_s_setprio(0); } while (0)
; #define PG8_WAIT_V(n) asm volatile("s_waitcnt vmcnt(" #n ")" ::: "memory")
; #define PG8_WAIT_L(n) asm volatile("s_waitcnt lgkmcnt(" #n ")" ::: "memory")
; #define PG8_BAR __builtin_amdgcn_s_barrier()
; #define PG8_SCHED __builtin_amdgcn_sched_barrier(0)
; template <class Epi, class Sched>
; __device__ __forceinline__ void gemm_phase(LAS unsigned char* lds, const Gemm g, const Sched& S, const Epi& E, const int tid) {
;     ...
;             PG8_WAIT_V(8); PG8_WAIT_L(0); PG8_BAR; PG8_MMA(0, 0, At, B0); PG8_MMA(0, 1, At, B1); PG8_BAR; PG8_SCHED;
;             PG8_LDA(At, 0, 1); PG8_STAGE(PG8_SB(0, 0), b2, voffB); PG8_STAGE(PG8_SB(0, 1), b2 + hstep, voffB); PG8_STAGE(PG8_SA(0, 0), a2, voffA);
;             PG8_WAIT_V(8); PG8_WAIT_L(0); PG8_BAR; PG8_MMA(1, 0, At, B0); PG8_MMA(1, 1, At, B1); PG8_BAR; PG8_SCHED;
;             PG8_LDB(B0, 1, 0); PG8_LDB(B1, 1, 1); PG8_SCHED; PG8_LDA(At, 1, 0); PG8_STAGE(PG8_SA(0, 1), a2 + hstep, voffA);
;             PG8_WAIT_V(8); PG8_WAIT_L(0); PG8_BAR; PG8_MMA(0, 0, At, B0); PG8_MMA(0, 1, At, B1); PG8_BAR; PG8_SCHED;
	s_setprio 1
	s_waitcnt lgkmcnt(0)
	v_mfma_f32_16x16x32_bf16 v[60:63], v[88:91], v[186:189], 0
	v_mfma_f32_16x16x32_bf16 v[56:59], v[144:147], v[186:189], 0
	v_mfma_f32_16x16x32_bf16 v[44:47], v[88:91], v[202:205], 0
	v_mfma_f32_16x16x32_bf16 v[40:43], v[144:147], v[202:205], 0
	v_mfma_f32_16x16x32_bf16 v[28:31], v[88:91], v[234:237], 0
	v_mfma_f32_16x16x32_bf16 v[24:27], v[144:147], v[234:237], 0
	v_mfma_f32_16x16x32_bf16 v[12:15], v[88:91], v[242:245], 0
	v_mfma_f32_16x16x32_bf16 v[8:11], v[144:147], v[242:245], 0
	v_mfma_f32_16x16x32_bf16 v[60:63], v[92:95], v[198:201], v[60:63]
	v_mfma_f32_16x16x32_bf16 v[56:59], v[148:151], v[198:201], v[56:59]
	v_mfma_f32_16x16x32_bf16 v[44:47], v[92:95], v[206:209], v[44:47]
	v_mfma_f32_16x16x32_bf16 v[40:43], v[148:151], v[206:209], v[40:43]
	v_mfma_f32_16x16x32_bf16 v[28:31], v[92:95], v[238:241], v[28:31]
	v_mfma_f32_16x16x32_bf16 v[24:27], v[148:151], v[238:241], v[24:27]
	v_mfma_f32_16x16x32_bf16 v[12:15], v[92:95], v[246:249], v[12:15]
	v_mfma_f32_16x16x32_bf16 v[8:11], v[148:151], v[246:249], v[8:11]
	s_setprio 0
	s_setprio 1
	v_mfma_f32_16x16x32_bf16 v[52:55], v[152:155], v[186:189], 0
	v_mfma_f32_16x16x32_bf16 v[48:51], v[178:181], v[186:189], 0
	v_mfma_f32_16x16x32_bf16 v[36:39], v[152:155], v[202:205], 0
	v_mfma_f32_16x16x32_bf16 v[32:35], v[178:181], v[202:205], 0
	v_mfma_f32_16x16x32_bf16 v[20:23], v[152:155], v[234:237], 0
	v_mfma_f32_16x16x32_bf16 v[16:19], v[178:181], v[234:237], 0
	v_mfma_f32_16x16x32_bf16 v[4:7], v[152:155], v[242:245], 0
	v_mfma_f32_16x16x32_bf16 v[0:3], v[178:181], v[242:245], 0
	v_mfma_f32_16x16x32_bf16 v[52:55], v[156:159], v[198:201], v[52:55]
	v_mfma_f32_16x16x32_bf16 v[48:51], v[182:185], v[198:201], v[48:51]
	v_mfma_f32_16x16x32_bf16 v[36:39], v[156:159], v[206:209], v[36:39]
	v_mfma_f32_16x16x32_bf16 v[32:35], v[182:185], v[206:209], v[32:35]
	v_mfma_f32_16x16x32_bf16 v[20:23], v[156:159], v[238:241], v[20:23]
	v_mfma_f32_16x16x32_bf16 v[16:19], v[182:185], v[238:241], v[16:19]
	v_mfma_f32_16x16x32_bf16 v[4:7], v[156:159], v[246:249], v[4:7]
	v_mfma_f32_16x16x32_bf16 v[0:3], v[182:185], v[246:249], v[0:3]
	s_setprio 0
	s_barrier
	s_add_i32 s61, 0, 0x18000
	v_add_u32_e32 v81, s61, v216
	s_add_i32 s70, 0, 0x1c000
	ds_read_b128 v[88:91], v81
	ds_read_b128 v[92:95], v81 offset:1024
	ds_read_b128 v[144:147], v81 offset:2048
	ds_read_b128 v[148:151], v81 offset:3072
	v_add_u32_e32 v81, s70, v216
	ds_read_b128 v[152:155], v81
	ds_read_b128 v[156:159], v81 offset:1024
	ds_read_b128 v[178:181], v81 offset:2048
	ds_read_b128 v[182:185], v81 offset:3072
	s_add_u32 s66, s66, 0x40000
	s_addc_u32 s67, s67, 0
	s_mov_b32 m0, s75
	v_lshl_add_u64 v[86:87], s[66:67], 0, v[162:163]
	ds_read_b128 v[186:189], v230 offset:32768
	ds_read_b128 v[198:201], v230 offset:33792
	ds_read_b128 v[202:205], v230 offset:34816
	ds_read_b128 v[206:209], v230 offset:35840
	ds_read_b128 v[234:237], v230 offset:36864
	ds_read_b128 v[238:241], v230 offset:37888
	ds_read_b128 v[242:245], v230 offset:38912
	ds_read_b128 v[246:249], v230 offset:39936
	global_load_lds_dwordx4 v[86:87], off
	v_lshl_add_u64 v[86:87], s[66:67], 0, v[166:167]
	s_mov_b32 m0, s81
	s_nop 0
	global_load_lds_dwordx4 v[86:87], off
	s_waitcnt vmcnt(8)
	s_waitcnt lgkmcnt(0)
	s_barrier
	s_setprio 1
	s_waitcnt lgkmcnt(0)
	v_mfma_f32_16x16x32_bf16 v[140:143], v[88:91], v[186:189], v[140:143]
	v_mfma_f32_16x16x32_bf16 v[136:139], v[144:147], v[186:189], v[136:139]
	v_mfma_f32_16x16x32_bf16 v[124:127], v[88:91], v[202:205], v[124:127]
	v_mfma_f32_16x16x32_bf16 v[120:123], v[144:147], v[202:205], v[120:123]
	v_mfma_f32_16x16x32_bf16 v[108:111], v[88:91], v[234:237], v[108:111]
	v_mfma_f32_16x16x32_bf16 v[104:107], v[144:147], v[234:237], v[104:107]
	v_mfma_f32_16x16x32_bf16 v[82:85], v[88:91], v[242:245], v[82:85]
	v_mfma_f32_16x16x32_bf16 v[76:79], v[144:147], v[242:245], v[76:79]
	v_mfma_f32_16x16x32_bf16 v[140:143], v[92:95], v[198:201], v[140:143]
	v_mfma_f32_16x16x32_bf16 v[136:139], v[148:151], v[198:201], v[136:139]
	v_mfma_f32_16x16x32_bf16 v[124:127], v[92:95], v[206:209], v[124:127]
	v_mfma_f32_16x16x32_bf16 v[120:123], v[148:151], v[206:209], v[120:123]
	v_mfma_f32_16x16x32_bf16 v[108:111], v[92:95], v[238:241], v[108:111]
	v_mfma_f32_16x16x32_bf16 v[104:107], v[148:151], v[238:241], v[104:107]
	v_mfma_f32_16x16x32_bf16 v[84:87], v[92:95], v[246:249], v[82:85]
	v_mfma_f32_16x16x32_bf16 v[76:79], v[148:151], v[246:249], v[76:79]
	s_setprio 0
	s_setprio 1
	v_mfma_f32_16x16x32_bf16 v[132:135], v[152:155], v[186:189], v[132:135]
	v_mfma_f32_16x16x32_bf16 v[128:131], v[178:181], v[186:189], v[128:131]
	v_mfma_f32_16x16x32_bf16 v[116:119], v[152:155], v[202:205], v[116:119]
	v_mfma_f32_16x16x32_bf16 v[112:115], v[178:181], v[202:205], v[112:115]
	v_mfma_f32_16x16x32_bf16 v[100:103], v[152:155], v[234:237], v[100:103]
	v_mfma_f32_16x16x32_bf16 v[96:99], v[178:181], v[234:237], v[96:99]
	v_mfma_f32_16x16x32_bf16 v[68:71], v[152:155], v[242:245], v[68:71]
	v_mfma_f32_16x16x32_bf16 v[64:67], v[178:181], v[242:245], v[64:67]
	v_mfma_f32_16x16x32_bf16 v[132:135], v[156:159], v[198:201], v[132:135]
	v_mfma_f32_16x16x32_bf16 v[128:131], v[182:185], v[198:201], v[128:131]
	v_mfma_f32_16x16x32_bf16 v[116:119], v[156:159], v[206:209], v[116:119]
	v_mfma_f32_16x16x32_bf16 v[112:115], v[182:185], v[206:209], v[112:115]
	v_mfma_f32_16x16x32_bf16 v[100:103], v[156:159], v[238:241], v[100:103]
	v_mfma_f32_16x16x32_bf16 v[96:99], v[182:185], v[238:241], v[96:99]
	v_mfma_f32_16x16x32_bf16 v[68:71], v[156:159], v[246:249], v[68:71]
	v_mfma_f32_16x16x32_bf16 v[64:67], v[182:185], v[246:249], v[64:67]
	s_setprio 0
	s_barrier
; #define PG8_STAGE(bufoff, gbase, voff) do { _Pragma("unroll") for (int _i = 0; _i < 2; ++_i) \
;         __builtin_amdgcn_global_load_lds((const unsigned*)((const char*)(gbase) + (voff)[_i]), (LAS unsigned*)(lds + (bufoff) + ldsw + _i * 8192), 16, 0, 0); } while (0)
; #define PG8_LDA(dst, b, h) do { _Pragma("unroll") for (int m = 0; m < 4; ++m) _Pragma("unroll") for (int k = 0; k < 2; ++k) dst[m][k] = *(const LAS bf16x8*)(lds + PG8_SA(b, h) + aoff + m * 2048 + k * 1024); } while (0)
; #define PG8_MMA(ai, bj, At, Bt) do { __builtin_amdgcn_s_setprio(1); _Pragma("unroll") for (int m = 0; m < 4; ++m) _Pragma("unroll") for (int n = 0; n < 2; ++n) _Pragma("unroll") for (int k = 0; k < 2; ++k) \
;         acc[ai][bj][m][n] = __builtin_amdgcn_mfma_f32_16x16x32_bf16(Bt[n][k], At[m][k], acc[ai][bj][m][n], 0, 0, 0); __builtin_amdgcn_s_setprio(0); } while (0)
; #define PG8_WAIT_V(n) asm volatile("s_waitcnt vmcnt(" #n ")" ::: "memory")
; #define PG8_WAIT_L(n) asm volatile("s_waitcnt lgkmcnt(" #n ")" ::: "memory")
; #define PG8_BAR __builtin_amdgcn_s_barrier()
; #define PG8_SCHED __builtin_amdgcn_sched_barrier(0)
; template <class Epi, class Sched>
; __device__ __forceinline__ void gemm_phase(LAS unsigned char* lds, const Gemm g, const Sched& S, const Epi& E, const int tid) {
;     ...
;             PG8_WAIT_V(8); PG8_WAIT_L(0); PG8_BAR; PG8_MMA(0, 0, At, B0); PG8_MMA(0, 1, At, B1); PG8_BAR; PG8_SCHED;
;             PG8_LDA(At, 1, 1); PG8_STAGE(PG8_SB(1, 0), b3, voffB); PG8_STAGE(PG8_SB(1, 1), b3 + hstep, voffB); PG8_STAGE(PG8_SA(1, 0), a3, voffA);
;             PG8_WAIT_V(8); PG8_WAIT_L(0); PG8_BAR; PG8_MMA(1, 0, At, B0); PG8_MMA(1, 1, At, B1); PG8_BAR; PG8_SCHED;
;         }
	s_add_i32 s61, s61, s12
	v_lshl_add_u64 v[82:83], v[190:191], 0, s[68:69]
	s_mov_b32 m0, s61
	ds_read_b128 v[186:189], v230 offset:49152
	ds_read_b128 v[198:201], v230 offset:50176
	ds_read_b128 v[202:205], v230 offset:51200
	ds_read_b128 v[206:209], v230 offset:52224
	ds_read_b128 v[234:237], v230 offset:53248
	ds_read_b128 v[238:241], v230 offset:54272
	ds_read_b128 v[242:245], v230 offset:55296
	ds_read_b128 v[246:249], v230 offset:56320
	global_load_lds_dwordx4 v[82:83], off
	s_add_i32 m0, s61, 0x2000
	s_add_u32 s64, s64, 0x40080
	v_lshl_add_u64 v[82:83], v[250:251], 0, s[68:69]
	s_addc_u32 s65, s65, 0
	s_add_i32 s61, s70, s12
	global_load_lds_dwordx4 v[82:83], off
	v_lshl_add_u64 v[82:83], s[64:65], 0, v[164:165]
	s_mov_b32 m0, s61
	s_nop 0
	global_load_lds_dwordx4 v[82:83], off
	v_lshl_add_u64 v[82:83], s[64:65], 0, v[168:169]
	s_add_i32 m0, s61, 0x2000
	s_nop 0
	global_load_lds_dwordx4 v[82:83], off
	v_lshl_add_u64 v[82:83], v[224:225], 0, s[68:69]
	s_mov_b32 m0, s82
	s_nop 0
	global_load_lds_dwordx4 v[82:83], off
	v_lshl_add_u64 v[82:83], v[226:227], 0, s[68:69]
	s_mov_b32 m0, s83
	s_nop 0
	global_load_lds_dwordx4 v[82:83], off
	s_waitcnt vmcnt(8)
	s_waitcnt lgkmcnt(0)
	s_barrier
	s_setprio 1
	s_waitcnt lgkmcnt(0)
	v_mfma_f32_16x16x32_bf16 v[60:63], v[88:91], v[186:189], v[60:63]
	v_mfma_f32_16x16x32_bf16 v[56:59], v[144:147], v[186:189], v[56:59]
	v_mfma_f32_16x16x32_bf16 v[44:47], v[88:91], v[202:205], v[44:47]
	v_mfma_f32_16x16x32_bf16 v[40:43], v[144:147], v[202:205], v[40:43]
	v_mfma_f32_16x16x32_bf16 v[28:31], v[88:91], v[234:237], v[28:31]
	v_mfma_f32_16x16x32_bf16 v[24:27], v[144:147], v[234:237], v[24:27]
	v_mfma_f32_16x16x32_bf16 v[12:15], v[88:91], v[242:245], v[12:15]
	v_mfma_f32_16x16x32_bf16 v[8:11], v[144:147], v[242:245], v[8:11]
	v_mfma_f32_16x16x32_bf16 v[60:63], v[92:95], v[198:201], v[60:63]
	v_mfma_f32_16x16x32_bf16 v[56:59], v[148:151], v[198:201], v[56:59]
	v_mfma_f32_16x16x32_bf16 v[44:47], v[92:95], v[206:209], v[44:47]
	v_mfma_f32_16x16x32_bf16 v[40:43], v[148:151], v[206:209], v[40:43]
	v_mfma_f32_16x16x32_bf16 v[28:31], v[92:95], v[238:241], v[28:31]
	v_mfma_f32_16x16x32_bf16 v[24:27], v[148:151], v[238:241], v[24:27]
	v_mfma_f32_16x16x32_bf16 v[12:15], v[92:95], v[246:249], v[12:15]
	v_mfma_f32_16x16x32_bf16 v[8:11], v[148:151], v[246:249], v[8:11]
	s_setprio 0
	s_setprio 1
	v_mfma_f32_16x16x32_bf16 v[52:55], v[152:155], v[186:189], v[52:55]
	v_mfma_f32_16x16x32_bf16 v[48:51], v[178:181], v[186:189], v[48:51]
	v_mfma_f32_16x16x32_bf16 v[36:39], v[152:155], v[202:205], v[36:39]
	v_mfma_f32_16x16x32_bf16 v[32:35], v[178:181], v[202:205], v[32:35]
	v_mfma_f32_16x16x32_bf16 v[20:23], v[152:155], v[234:237], v[20:23]
	v_mfma_f32_16x16x32_bf16 v[16:19], v[178:181], v[234:237], v[16:19]
	v_mfma_f32_16x16x32_bf16 v[4:7], v[152:155], v[242:245], v[4:7]
	v_mfma_f32_16x16x32_bf16 v[0:3], v[178:181], v[242:245], v[0:3]
	v_mfma_f32_16x16x32_bf16 v[52:55], v[156:159], v[198:201], v[52:55]
	v_mfma_f32_16x16x32_bf16 v[48:51], v[182:185], v[198:201], v[48:51]
	v_mfma_f32_16x16x32_bf16 v[36:39], v[156:159], v[206:209], v[36:39]
	v_mfma_f32_16x16x32_bf16 v[32:35], v[182:185], v[206:209], v[32:35]
	v_mfma_f32_16x16x32_bf16 v[20:23], v[156:159], v[238:241], v[20:23]
	v_mfma_f32_16x16x32_bf16 v[16:19], v[182:185], v[238:241], v[16:19]
	v_mfma_f32_16x16x32_bf16 v[4:7], v[156:159], v[246:249], v[4:7]
	v_mfma_f32_16x16x32_bf16 v[0:3], v[182:185], v[246:249], v[0:3]
	s_setprio 0
	s_barrier
	s_add_i32 s60, s60, 2
	s_add_u32 s6, s6, 0x100
	s_addc_u32 s7, s7, 0
	s_add_u32 s58, s58, 0x100
	s_addc_u32 s59, s59, 0
	s_cmp_gt_u32 s60, 13

; #define LAS __attribute__((address_space(3)))
; __device__ __forceinline__ void prenorm_commit(const PreNorm& p, LAS float* scr, int tid) {
;     if (tid < 256) { scr[tid] = rsqrtf(((p.st[0] + p.st[1]) + (p.st[2] + p.st[3])) * (1.0f / DM) + EPS); scr[256 + tid] = p.sw; }
;     asm volatile("s_waitcnt lgkmcnt(0)" ::: "memory"); __builtin_amdgcn_s_barrier(); asm volatile("" ::: "memory");
.LBB0_269:
	s_and_saveexec_b64 s[6:7], s[8:9]
	s_cbranch_execz .LBB0_271
	s_waitcnt vmcnt(8)
	v_mov_b32_e32 v82, v73
	v_mov_b32_e32 v83, v74
	v_mov_b32_e32 v73, v75
	v_pk_add_f32 v[72:73], v[82:83], v[72:73]
	s_nop 0
	v_add_f32_e32 v72, v72, v73
	v_fmamk_f32 v72, v72, 0x3a800000, v222
	v_mul_f32_e32 v73, 0x4b800000, v72
	v_cmp_gt_f32_e32 vcc, s45, v72
	s_nop 1
	v_cndmask_b32_e32 v72, v72, v73, vcc
	v_rsq_f32_e32 v72, v72
	s_nop 0
	v_mul_f32_e32 v73, 0x45800000, v72
	v_cndmask_b32_e32 v72, v72, v73, vcc
	ds_write2st64_b32 v217, v72, v80 offset1:4

;     __device__ __forceinline__ Pre prefetch(const Unit& u, int tid) const { return prenorm_load(stats, u.pn * BM, sW + (size_t)(u.pn >> 4) * SW_ROWS + u.pm * BM, tid); }
;     __device__ __forceinline__ Pre prefetch(const Unit& u, int tid) const { return prenorm_load(stats, u.pm * BM, sW + (size_t)(u.pm >> 4) * SW_ROWS + u.pn * BM, tid); }
;     __device__ __forceinline__ Pre prefetch(const Unit& u, int tid) const { return prenorm_load(stats, u.pm * BM, sW + (size_t)(u.pm >> 4) * SW_ROWS + u.pn * BM, tid); }
; #define PG8_STAGE(bufoff, gbase, voff) do { _Pragma("unroll") for (int _i = 0; _i < 2; ++_i) \
;         __builtin_amdgcn_global_load_lds((const unsigned*)((const char*)(gbase) + (voff)[_i]), (LAS unsigned*)(lds + (bufoff) + ldsw + _i * 8192), 16, 0, 0); } while (0)
; #define PG8_LDA(dst, b, h) do { _Pragma("unroll") for (int m = 0; m < 4; ++m) _Pragma("unroll") for (int k = 0; k < 2; ++k) dst[m][k] = *(const LAS bf16x8*)(lds + PG8_SA(b, h) + aoff + m * 2048 + k * 1024); } while (0)
; #define PG8_LDB(dst, b, h) do { _Pragma("unroll") for (int n = 0; n < 2; ++n) _Pragma("unroll") for (int k = 0; k < 2; ++k) dst[n][k] = *(const LAS bf16x8*)(lds + PG8_SB(b, h) + boff + n * 2048 + k * 1024); } while (0)
; #define PG8_WAIT_V(n) asm volatile("s_waitcnt vmcnt(" #n ")" ::: "memory")
; template <class Epi, class Sched>
; __device__ __forceinline__ void gemm_phase(LAS unsigned char* lds, const Gemm g, const Sched& S, const Epi& E, const int tid) {
;     ...
;     for (;;) {
;         const bool has_next = S.next(ui + 1, nxt);
;         const char* nA = has_next ? (const char*)g.A + (size_t)nxt.pm * tstep : cA; const char* nB = has_next ? (const char*)g.Bt + (size_t)nxt.pn * tstep : cB;
;         const typename Epi::Pre pre = E.prefetch(cur, tid);
;         for (int t = 0; t < nt; t += 2) {
;             const bool last = (t == nt - 2);
;             const char* a1 = cA + (size_t)(t + 1) * kstep;
;             const char* a2 = last ? nA : cA + (size_t)(t + 2) * kstep; const char* b2 = last ? nB : cB + (size_t)(t + 2) * kstep;
;             const char* a3 = a2 + kstep; const char* b3 = b2 + kstep;
;             PG8_LDB(B0, 0, 0); PG8_LDB(B1, 0, 1); PG8_SCHED; PG8_LDA(At, 0, 0); PG8_STAGE(PG8_SA(1, 1), a1 + hstep, voffA);
;             PG8_WAIT_V(8); PG8_WAIT_L(0); PG8_BAR; PG8_MMA(0, 0, At, B0); PG8_MMA(0, 1, At, B1); PG8_BAR; PG8_SCHED;
.LBB0_325:
	s_or_b64 exec, exec, s[50:51]
	s_ashr_i32 s39, s38, 31
	s_lshl_b64 s[50:51], s[38:39], 19
	s_add_u32 s50, s85, s50
	s_addc_u32 s51, s86, s51
	s_and_b64 s[54:55], s[4:5], exec
	s_cselect_b32 s39, s51, s63
	s_cselect_b32 s74, s50, s62
	s_ashr_i32 s23, s22, 31
	s_lshl_b64 s[54:55], s[22:23], 19
	s_add_u32 s54, s46, s54
	s_addc_u32 s55, s47, s55
	s_and_b64 s[66:67], s[4:5], exec
	s_cselect_b32 s23, s55, s65
	s_cselect_b32 s75, s54, s64
	s_add_u32 s62, s62, 0x40080
	s_addc_u32 s63, s63, 0
	s_add_u32 s78, s64, 0x100
	s_addc_u32 s79, s65, 0
	s_mov_b32 s81, -2
	s_waitcnt lgkmcnt(0)
	s_add_u32 s64, s62, 0xfffc0080
	s_addc_u32 s65, s63, -1
	s_add_i32 s82, 0, 0x10000
	s_cmp_eq_u32 s81, 12
	s_cselect_b32 s67, s39, s65
	s_cselect_b32 s66, s74, s64
	v_add_u32_e32 v69, s82, v154
	s_cselect_b32 s65, s23, s79
	s_cselect_b32 s64, s75, s78
	s_add_i32 s90, 0, 0x14000
	ds_read_b128 v[70:73], v69
	ds_read_b128 v[74:77], v69 offset:1024
	ds_read_b128 v[172:175], v69 offset:2048
	ds_read_b128 v[176:179], v69 offset:3072
	v_add_u32_e32 v69, s90, v154
	ds_read_b128 v[180:183], v69
	ds_read_b128 v[184:187], v69 offset:1024
	ds_read_b128 v[188:191], v69 offset:2048
	ds_read_b128 v[198:201], v69 offset:3072
	v_lshl_add_u64 v[78:79], s[62:63], 0, v[144:145]
	s_add_i32 m0, s53, 0xc000
	ds_read_b128 v[202:205], v171
	ds_read_b128 v[206:209], v171 offset:1024
	ds_read_b128 v[210:213], v171 offset:2048
	ds_read_b128 v[214:217], v171 offset:3072
	ds_read_b128 v[218:221], v171 offset:4096
	ds_read_b128 v[230:233], v171 offset:5120
	ds_read_b128 v[234:237], v171 offset:6144
	ds_read_b128 v[238:241], v171 offset:7168
	global_load_lds_dwordx4 v[78:79], off
	v_lshl_add_u64 v[78:79], s[62:63], 0, v[146:147]
	s_add_i32 m0, s53, 0xe000
	s_nop 0
	global_load_lds_dwordx4 v[78:79], off
	s_waitcnt vmcnt(8)
	s_waitcnt lgkmcnt(0)
	s_barrier
	s_setprio 1
	s_waitcnt lgkmcnt(0)
	v_mfma_f32_16x16x32_bf16 v[140:143], v[70:73], v[202:205], 0
	v_mfma_f32_16x16x32_bf16 v[136:139], v[172:175], v[202:205], 0
	v_mfma_f32_16x16x32_bf16 v[132:135], v[70:73], v[210:213], 0
	v_mfma_f32_16x16x32_bf16 v[128:131], v[172:175], v[210:213], 0
	v_mfma_f32_16x16x32_bf16 v[116:119], v[70:73], v[218:221], 0
	v_mfma_f32_16x16x32_bf16 v[112:115], v[172:175], v[218:221], 0
	v_mfma_f32_16x16x32_bf16 v[100:103], v[70:73], v[234:237], 0
	v_mfma_f32_16x16x32_bf16 v[96:99], v[172:175], v[234:237], 0
	v_mfma_f32_16x16x32_bf16 v[140:143], v[74:77], v[206:209], v[140:143]
	v_mfma_f32_16x16x32_bf16 v[136:139], v[176:179], v[206:209], v[136:139]
	v_mfma_f32_16x16x32_bf16 v[132:135], v[74:77], v[214:217], v[132:135]
	v_mfma_f32_16x16x32_bf16 v[128:131], v[176:179], v[214:217], v[128:131]
	v_mfma_f32_16x16x32_bf16 v[116:119], v[74:77], v[230:233], v[116:119]
	v_mfma_f32_16x16x32_bf16 v[112:115], v[176:179], v[230:233], v[112:115]
	v_mfma_f32_16x16x32_bf16 v[100:103], v[74:77], v[238:241], v[100:103]
	v_mfma_f32_16x16x32_bf16 v[96:99], v[176:179], v[238:241], v[96:99]
	s_setprio 0
	s_setprio 1
	v_mfma_f32_16x16x32_bf16 v[124:127], v[180:183], v[202:205], 0
	v_mfma_f32_16x16x32_bf16 v[120:123], v[188:191], v[202:205], 0
	v_mfma_f32_16x16x32_bf16 v[108:111], v[180:183], v[210:213], 0
	v_mfma_f32_16x16x32_bf16 v[104:107], v[188:191], v[210:213], 0
	v_mfma_f32_16x16x32_bf16 v[92:95], v[180:183], v[218:221], 0
	v_mfma_f32_16x16x32_bf16 v[88:91], v[188:191], v[218:221], 0
	v_mfma_f32_16x16x32_bf16 v[84:87], v[180:183], v[234:237], 0
	v_mfma_f32_16x16x32_bf16 v[78:81], v[188:191], v[234:237], 0
	v_mfma_f32_16x16x32_bf16 v[124:127], v[184:187], v[206:209], v[124:127]
	v_mfma_f32_16x16x32_bf16 v[120:123], v[198:201], v[206:209], v[120:123]
	v_mfma_f32_16x16x32_bf16 v[108:111], v[184:187], v[214:217], v[108:111]
	v_mfma_f32_16x16x32_bf16 v[104:107], v[198:201], v[214:217], v[104:107]
	v_mfma_f32_16x16x32_bf16 v[92:95], v[184:187], v[230:233], v[92:95]
	v_mfma_f32_16x16x32_bf16 v[88:91], v[198:201], v[230:233], v[88:91]
	v_mfma_f32_16x16x32_bf16 v[84:87], v[184:187], v[238:241], v[84:87]
	v_mfma_f32_16x16x32_bf16 v[78:81], v[198:201], v[238:241], v[78:81]
	s_setprio 0
	s_barrier
	s_add_i32 s82, s82, s52
	v_lshl_add_u64 v[224:225], s[64:65], 0, v[164:165]
	s_mov_b32 m0, s82
	ds_read_b128 v[202:205], v171 offset:16384
	ds_read_b128 v[206:209], v171 offset:17408
	ds_read_b128 v[210:213], v171 offset:18432
	ds_read_b128 v[214:217], v171 offset:19456
	ds_read_b128 v[218:221], v171 offset:20480
	ds_read_b128 v[230:233], v171 offset:21504
	ds_read_b128 v[234:237], v171 offset:22528
	ds_read_b128 v[238:241], v171 offset:23552
	global_load_lds_dwordx4 v[224:225], off
	s_add_i32 m0, s82, 0x2000
	s_add_u32 s82, s64, 0x40000
	v_lshl_add_u64 v[226:227], s[64:65], 0, v[168:169]
	s_addc_u32 s83, s65, 0
	s_add_i32 s90, s90, s52
	global_load_lds_dwordx4 v[226:227], off
	v_lshl_add_u64 v[82:83], s[82:83], 0, v[164:165]
	s_mov_b32 m0, s90
	v_lshl_add_u64 v[242:243], s[66:67], 0, v[162:163]
	global_load_lds_dwordx4 v[82:83], off
	v_lshl_add_u64 v[82:83], s[82:83], 0, v[168:169]
	s_add_i32 m0, s90, 0x2000
	v_lshl_add_u64 v[244:245], s[66:67], 0, v[166:167]
	global_load_lds_dwordx4 v[82:83], off
	s_mov_b32 m0, s53
	s_nop 0
	global_load_lds_dwordx4 v[242:243], off
	s_mov_b32 m0, s56
	s_nop 0
	global_load_lds_dwordx4 v[244:245], off
	s_waitcnt vmcnt(8)
	s_waitcnt lgkmcnt(0)
	s_barrier
; #define PG8_STAGE(bufoff, gbase, voff) do { _Pragma("unroll") for (int _i = 0; _i < 2; ++_i) \
;         __builtin_amdgcn_global_load_lds((const unsigned*)((const char*)(gbase) + (voff)[_i]), (LAS unsigned*)(lds + (bufoff) + ldsw + _i * 8192), 16, 0, 0); } while (0)
; #define PG8_LDA(dst, b, h) do { _Pragma("unroll") for (int m = 0; m < 4; ++m) _Pragma("unroll") for (int k = 0; k < 2; ++k) dst[m][k] = *(const LAS bf16x8*)(lds + PG8_SA(b, h) + aoff + m * 2048 + k * 1024); } while (0)
; #define PG8_LDB(dst, b, h) do { _Pragma("unroll") for (int n = 0; n < 2; ++n) _Pragma("unroll") for (int k = 0; k < 2; ++k) dst[n][k] = *(const LAS bf16x8*)(lds + PG8_SB(b, h) + boff + n * 2048 + k * 1024); } while (0)
; #define PG8_MMA(ai, bj, At, Bt) do { __builtin_amdgcn_s_setprio(1); _Pragma("unroll") for (int m = 0; m < 4; ++m) _Pragma("unroll") for (int n = 0; n < 2; ++n) _Pragma("unroll") for (int k = 0; k < 2; ++k) \
;         acc[ai][bj][m][n] = __builtin_amdgcn_mfma_f32_16x16x32_bf16(Bt[n][k], At[m][k], acc[ai][bj][m][n], 0, 0, 0); __builtin_amdgcn_s_setprio(0); } while (0)
; #define PG8_WAIT_V(n) asm volatile("s_waitcnt vmcnt(" #n ")" ::: "memory")
; #define PG8_WAIT_L(n) asm volatile("s_waitcnt lgkmcnt(" #n ")" ::: "memory")
; #define PG8_BAR __builtin_amdgcn_s_barrier()
; #define PG8_SCHED __builtin_amdgcn_sched_barrier(0)
; template <class Epi, class Sched>
; __device__ __forceinline__ void gemm_phase(LAS unsigned char* lds, const Gemm g, const Sched& S, const Epi& E, const int tid) {
;     ...
;             PG8_WAIT_V(8); PG8_WAIT_L(0); PG8_BAR; PG8_MMA(0, 0, At, B0); PG8_MMA(0, 1, At, B1); PG8_BAR; PG8_SCHED;
;             PG8_LDA(At, 0, 1); PG8_STAGE(PG8_SB(0, 0), b2, voffB); PG8_STAGE(PG8_SB(0, 1), b2 + hstep, voffB); PG8_STAGE(PG8_SA(0, 0), a2, voffA);
;             PG8_WAIT_V(8); PG8_WAIT_L(0); PG8_BAR; PG8_MMA(1, 0, At, B0); PG8_MMA(1, 1, At, B1); PG8_BAR; PG8_SCHED;
;             PG8_LDB(B0, 1, 0); PG8_LDB(B1, 1, 1); PG8_SCHED; PG8_LDA(At, 1, 0); PG8_STAGE(PG8_SA(0, 1), a2 + hstep, voffA);
;             PG8_WAIT_V(8); PG8_WAIT_L(0); PG8_BAR; PG8_MMA(0, 0, At, B0); PG8_MMA(0, 1, At, B1); PG8_BAR; PG8_SCHED;
	s_setprio 1
	s_waitcnt lgkmcnt(0)
	v_mfma_f32_16x16x32_bf16 v[60:63], v[70:73], v[202:205], 0
	v_mfma_f32_16x16x32_bf16 v[56:59], v[172:175], v[202:205], 0
	v_mfma_f32_16x16x32_bf16 v[52:55], v[70:73], v[210:213], 0
	v_mfma_f32_16x16x32_bf16 v[44:47], v[172:175], v[210:213], 0
	v_mfma_f32_16x16x32_bf16 v[28:31], v[70:73], v[218:221], 0
	v_mfma_f32_16x16x32_bf16 v[24:27], v[172:175], v[218:221], 0
	v_mfma_f32_16x16x32_bf16 v[16:19], v[70:73], v[234:237], 0
	v_mfma_f32_16x16x32_bf16 v[8:11], v[172:175], v[234:237], 0
	v_mfma_f32_16x16x32_bf16 v[60:63], v[74:77], v[206:209], v[60:63]
	v_mfma_f32_16x16x32_bf16 v[56:59], v[176:179], v[206:209], v[56:59]
	v_mfma_f32_16x16x32_bf16 v[52:55], v[74:77], v[214:217], v[52:55]
	v_mfma_f32_16x16x32_bf16 v[44:47], v[176:179], v[214:217], v[44:47]
	v_mfma_f32_16x16x32_bf16 v[28:31], v[74:77], v[230:233], v[28:31]
	v_mfma_f32_16x16x32_bf16 v[24:27], v[176:179], v[230:233], v[24:27]
	v_mfma_f32_16x16x32_bf16 v[16:19], v[74:77], v[238:241], v[16:19]
	v_mfma_f32_16x16x32_bf16 v[8:11], v[176:179], v[238:241], v[8:11]
	s_setprio 0
	s_setprio 1
	v_mfma_f32_16x16x32_bf16 v[48:51], v[180:183], v[202:205], 0
	v_mfma_f32_16x16x32_bf16 v[40:43], v[188:191], v[202:205], 0
	v_mfma_f32_16x16x32_bf16 v[36:39], v[180:183], v[210:213], 0
	v_mfma_f32_16x16x32_bf16 v[32:35], v[188:191], v[210:213], 0
	v_mfma_f32_16x16x32_bf16 v[20:23], v[180:183], v[218:221], 0
	v_mfma_f32_16x16x32_bf16 v[12:15], v[188:191], v[218:221], 0
	v_mfma_f32_16x16x32_bf16 v[4:7], v[180:183], v[234:237], 0
	v_mfma_f32_16x16x32_bf16 v[0:3], v[188:191], v[234:237], 0
	v_mfma_f32_16x16x32_bf16 v[48:51], v[184:187], v[206:209], v[48:51]
	v_mfma_f32_16x16x32_bf16 v[40:43], v[198:201], v[206:209], v[40:43]
	v_mfma_f32_16x16x32_bf16 v[36:39], v[184:187], v[214:217], v[36:39]
	v_mfma_f32_16x16x32_bf16 v[32:35], v[198:201], v[214:217], v[32:35]
	v_mfma_f32_16x16x32_bf16 v[20:23], v[184:187], v[230:233], v[20:23]
	v_mfma_f32_16x16x32_bf16 v[12:15], v[198:201], v[230:233], v[12:15]
	v_mfma_f32_16x16x32_bf16 v[4:7], v[184:187], v[238:241], v[4:7]
	v_mfma_f32_16x16x32_bf16 v[0:3], v[198:201], v[238:241], v[0:3]
	s_setprio 0
	s_barrier
	s_add_i32 s82, 0, 0x18000
	v_add_u32_e32 v69, s82, v154
	s_add_i32 s83, 0, 0x1c000
	ds_read_b128 v[70:73], v69
	ds_read_b128 v[74:77], v69 offset:1024
	ds_read_b128 v[172:175], v69 offset:2048
	ds_read_b128 v[176:179], v69 offset:3072
	v_add_u32_e32 v69, s83, v154
	ds_read_b128 v[180:183], v69
	ds_read_b128 v[184:187], v69 offset:1024
	ds_read_b128 v[188:191], v69 offset:2048
	ds_read_b128 v[198:201], v69 offset:3072
	s_add_u32 s66, s66, 0x40000
	s_addc_u32 s67, s67, 0
	s_mov_b32 m0, s57
	v_lshl_add_u64 v[82:83], s[66:67], 0, v[162:163]
	ds_read_b128 v[202:205], v171 offset:32768
	ds_read_b128 v[206:209], v171 offset:33792
	ds_read_b128 v[210:213], v171 offset:34816
	ds_read_b128 v[214:217], v171 offset:35840
	ds_read_b128 v[218:221], v171 offset:36864
	ds_read_b128 v[230:233], v171 offset:37888
	ds_read_b128 v[234:237], v171 offset:38912
	ds_read_b128 v[238:241], v171 offset:39936
	global_load_lds_dwordx4 v[82:83], off
	v_lshl_add_u64 v[82:83], s[66:67], 0, v[166:167]
	s_mov_b32 m0, s58
	s_nop 0
	global_load_lds_dwordx4 v[82:83], off
	s_waitcnt vmcnt(8)
	s_waitcnt lgkmcnt(0)
	s_barrier
	s_setprio 1
	s_waitcnt lgkmcnt(0)
	v_mfma_f32_16x16x32_bf16 v[140:143], v[70:73], v[202:205], v[140:143]
	v_mfma_f32_16x16x32_bf16 v[136:139], v[172:175], v[202:205], v[136:139]
	v_mfma_f32_16x16x32_bf16 v[132:135], v[70:73], v[210:213], v[132:135]
	v_mfma_f32_16x16x32_bf16 v[128:131], v[172:175], v[210:213], v[128:131]
	v_mfma_f32_16x16x32_bf16 v[116:119], v[70:73], v[218:221], v[116:119]
	v_mfma_f32_16x16x32_bf16 v[112:115], v[172:175], v[218:221], v[112:115]
	v_mfma_f32_16x16x32_bf16 v[100:103], v[70:73], v[234:237], v[100:103]
	v_mfma_f32_16x16x32_bf16 v[96:99], v[172:175], v[234:237], v[96:99]
	v_mfma_f32_16x16x32_bf16 v[140:143], v[74:77], v[206:209], v[140:143]
	v_mfma_f32_16x16x32_bf16 v[136:139], v[176:179], v[206:209], v[136:139]
	v_mfma_f32_16x16x32_bf16 v[132:135], v[74:77], v[214:217], v[132:135]
	v_mfma_f32_16x16x32_bf16 v[128:131], v[176:179], v[214:217], v[128:131]
	v_mfma_f32_16x16x32_bf16 v[116:119], v[74:77], v[230:233], v[116:119]
	v_mfma_f32_16x16x32_bf16 v[112:115], v[176:179], v[230:233], v[112:115]
	v_mfma_f32_16x16x32_bf16 v[100:103], v[74:77], v[238:241], v[100:103]
	v_mfma_f32_16x16x32_bf16 v[96:99], v[176:179], v[238:241], v[96:99]
	s_setprio 0
	s_setprio 1
	v_mfma_f32_16x16x32_bf16 v[124:127], v[180:183], v[202:205], v[124:127]
	v_mfma_f32_16x16x32_bf16 v[120:123], v[188:191], v[202:205], v[120:123]
	v_mfma_f32_16x16x32_bf16 v[108:111], v[180:183], v[210:213], v[108:111]
	v_mfma_f32_16x16x32_bf16 v[104:107], v[188:191], v[210:213], v[104:107]
	v_mfma_f32_16x16x32_bf16 v[92:95], v[180:183], v[218:221], v[92:95]
	v_mfma_f32_16x16x32_bf16 v[88:91], v[188:191], v[218:221], v[88:91]
	v_mfma_f32_16x16x32_bf16 v[82:85], v[180:183], v[234:237], v[84:87]
	v_mfma_f32_16x16x32_bf16 v[78:81], v[188:191], v[234:237], v[78:81]
	v_mfma_f32_16x16x32_bf16 v[124:127], v[184:187], v[206:209], v[124:127]
	v_mfma_f32_16x16x32_bf16 v[120:123], v[198:201], v[206:209], v[120:123]
	v_mfma_f32_16x16x32_bf16 v[108:111], v[184:187], v[214:217], v[108:111]
	v_mfma_f32_16x16x32_bf16 v[104:107], v[198:201], v[214:217], v[104:107]
	v_mfma_f32_16x16x32_bf16 v[92:95], v[184:187], v[230:233], v[92:95]
	v_mfma_f32_16x16x32_bf16 v[88:91], v[198:201], v[230:233], v[88:91]
	v_mfma_f32_16x16x32_bf16 v[84:87], v[184:187], v[238:241], v[82:85]
	v_mfma_f32_16x16x32_bf16 v[80:83], v[198:201], v[238:241], v[78:81]
	s_setprio 0
	s_barrier
; #define PG8_STAGE(bufoff, gbase, voff) do { _Pragma("unroll") for (int _i = 0; _i < 2; ++_i) \
;         __builtin_amdgcn_global_load_lds((const unsigned*)((const char*)(gbase) + (voff)[_i]), (LAS unsigned*)(lds + (bufoff) + ldsw + _i * 8192), 16, 0, 0); } while (0)
; #define PG8_LDA(dst, b, h) do { _Pragma("unroll") for (int m = 0; m < 4; ++m) _Pragma("unroll") for (int k = 0; k < 2; ++k) dst[m][k] = *(const LAS bf16x8*)(lds + PG8_SA(b, h) + aoff + m * 2048 + k * 1024); } while (0)
; #define PG8_MMA(ai, bj, At, Bt) do { __builtin_amdgcn_s_setprio(1); _Pragma("unroll") for (int m = 0; m < 4; ++m) _Pragma("unroll") for (int n = 0; n < 2; ++n) _Pragma("unroll") for (int k = 0; k < 2; ++k) \
;         acc[ai][bj][m][n] = __builtin_amdgcn_mfma_f32_16x16x32_bf16(Bt[n][k], At[m][k], acc[ai][bj][m][n], 0, 0, 0); __builtin_amdgcn_s_setprio(0); } while (0)
; #define PG8_WAIT_V(n) asm volatile("s_waitcnt vmcnt(" #n ")" ::: "memory")
; #define PG8_WAIT_L(n) asm volatile("s_waitcnt lgkmcnt(" #n ")" ::: "memory")
; #define PG8_BAR __builtin_amdgcn_s_barrier()
; #define PG8_SCHED __builtin_amdgcn_sched_barrier(0)
; template <class Epi, class Sched>
; __device__ __forceinline__ void gemm_phase(LAS unsigned char* lds, const Gemm g, const Sched& S, const Epi& E, const int tid) {
;     ...
;             PG8_WAIT_V(8); PG8_WAIT_L(0); PG8_BAR; PG8_MMA(0, 0, At, B0); PG8_MMA(0, 1, At, B1); PG8_BAR; PG8_SCHED;
;             PG8_LDA(At, 1, 1); PG8_STAGE(PG8_SB(1, 0), b3, voffB); PG8_STAGE(PG8_SB(1, 1), b3 + hstep, voffB); PG8_STAGE(PG8_SA(1, 0), a3, voffA);
;             PG8_WAIT_V(8); PG8_WAIT_L(0); PG8_BAR; PG8_MMA(1, 0, At, B0); PG8_MMA(1, 1, At, B1); PG8_BAR; PG8_SCHED;
;         }
	s_add_i32 s66, s82, s52
	v_lshl_add_u64 v[78:79], v[224:225], 0, s[68:69]
	s_mov_b32 m0, s66
	ds_read_b128 v[202:205], v171 offset:49152
	ds_read_b128 v[206:209], v171 offset:50176
	ds_read_b128 v[210:213], v171 offset:51200
	ds_read_b128 v[214:217], v171 offset:52224
	ds_read_b128 v[218:221], v171 offset:53248
	ds_read_b128 v[230:233], v171 offset:54272
	ds_read_b128 v[234:237], v171 offset:55296
	ds_read_b128 v[238:241], v171 offset:56320
	global_load_lds_dwordx4 v[78:79], off
	s_add_i32 m0, s66, 0x2000
	s_add_u32 s64, s64, 0x40080
	v_lshl_add_u64 v[78:79], v[226:227], 0, s[68:69]
	s_addc_u32 s65, s65, 0
	s_add_i32 s66, s83, s52
	global_load_lds_dwordx4 v[78:79], off
	v_lshl_add_u64 v[78:79], s[64:65], 0, v[164:165]
	s_mov_b32 m0, s66
	s_nop 0
	global_load_lds_dwordx4 v[78:79], off
	v_lshl_add_u64 v[78:79], s[64:65], 0, v[168:169]
	s_add_i32 m0, s66, 0x2000
	s_nop 0
	global_load_lds_dwordx4 v[78:79], off
	v_lshl_add_u64 v[78:79], v[242:243], 0, s[68:69]
	s_mov_b32 m0, s61
	s_nop 0
	global_load_lds_dwordx4 v[78:79], off
	v_lshl_add_u64 v[78:79], v[244:245], 0, s[68:69]
	s_mov_b32 m0, s70
	s_nop 0
	global_load_lds_dwordx4 v[78:79], off
	s_waitcnt vmcnt(8)
	s_waitcnt lgkmcnt(0)
	s_barrier
	s_setprio 1
	s_waitcnt lgkmcnt(0)
	v_mfma_f32_16x16x32_bf16 v[60:63], v[70:73], v[202:205], v[60:63]
	v_mfma_f32_16x16x32_bf16 v[56:59], v[172:175], v[202:205], v[56:59]
	v_mfma_f32_16x16x32_bf16 v[52:55], v[70:73], v[210:213], v[52:55]
	v_mfma_f32_16x16x32_bf16 v[44:47], v[172:175], v[210:213], v[44:47]
	v_mfma_f32_16x16x32_bf16 v[28:31], v[70:73], v[218:221], v[28:31]
	v_mfma_f32_16x16x32_bf16 v[24:27], v[172:175], v[218:221], v[24:27]
	v_mfma_f32_16x16x32_bf16 v[16:19], v[70:73], v[234:237], v[16:19]
	v_mfma_f32_16x16x32_bf16 v[8:11], v[172:175], v[234:237], v[8:11]
	v_mfma_f32_16x16x32_bf16 v[60:63], v[74:77], v[206:209], v[60:63]
	v_mfma_f32_16x16x32_bf16 v[56:59], v[176:179], v[206:209], v[56:59]
	v_mfma_f32_16x16x32_bf16 v[52:55], v[74:77], v[214:217], v[52:55]
	v_mfma_f32_16x16x32_bf16 v[44:47], v[176:179], v[214:217], v[44:47]
	v_mfma_f32_16x16x32_bf16 v[28:31], v[74:77], v[230:233], v[28:31]
	v_mfma_f32_16x16x32_bf16 v[24:27], v[176:179], v[230:233], v[24:27]
	v_mfma_f32_16x16x32_bf16 v[16:19], v[74:77], v[238:241], v[16:19]
	v_mfma_f32_16x16x32_bf16 v[8:11], v[176:179], v[238:241], v[8:11]
	s_setprio 0
	s_setprio 1
	v_mfma_f32_16x16x32_bf16 v[48:51], v[180:183], v[202:205], v[48:51]
	v_mfma_f32_16x16x32_bf16 v[40:43], v[188:191], v[202:205], v[40:43]
	v_mfma_f32_16x16x32_bf16 v[36:39], v[180:183], v[210:213], v[36:39]
	v_mfma_f32_16x16x32_bf16 v[32:35], v[188:191], v[210:213], v[32:35]
	v_mfma_f32_16x16x32_bf16 v[20:23], v[180:183], v[218:221], v[20:23]
	v_mfma_f32_16x16x32_bf16 v[12:15], v[188:191], v[218:221], v[12:15]
	v_mfma_f32_16x16x32_bf16 v[4:7], v[180:183], v[234:237], v[4:7]
	v_mfma_f32_16x16x32_bf16 v[0:3], v[188:191], v[234:237], v[0:3]
	v_mfma_f32_16x16x32_bf16 v[48:51], v[184:187], v[206:209], v[48:51]
	v_mfma_f32_16x16x32_bf16 v[40:43], v[198:201], v[206:209], v[40:43]
	v_mfma_f32_16x16x32_bf16 v[36:39], v[184:187], v[214:217], v[36:39]
	v_mfma_f32_16x16x32_bf16 v[32:35], v[198:201], v[214:217], v[32:35]
	v_mfma_f32_16x16x32_bf16 v[20:23], v[184:187], v[230:233], v[20:23]
	v_mfma_f32_16x16x32_bf16 v[12:15], v[198:201], v[230:233], v[12:15]
	v_mfma_f32_16x16x32_bf16 v[4:7], v[184:187], v[238:241], v[4:7]
	v_mfma_f32_16x16x32_bf16 v[0:3], v[198:201], v[238:241], v[0:3]
	s_setprio 0
	s_barrier
	s_add_i32 s81, s81, 2
	s_add_u32 s62, s62, 0x100
	s_addc_u32 s63, s63, 0
	s_add_u32 s78, s78, 0x100
	s_addc_u32 s79, s79, 0
	s_cmp_gt_u32 s81, 13

; #define LAS __attribute__((address_space(3)))
; __device__ __forceinline__ void prenorm_commit(const PreNorm& p, LAS float* scr, int tid) {
;     if (tid < 256) { scr[tid] = rsqrtf(((p.st[0] + p.st[1]) + (p.st[2] + p.st[3])) * (1.0f / DM) + EPS); scr[256 + tid] = p.sw; }
;     asm volatile("s_waitcnt lgkmcnt(0)" ::: "memory"); __builtin_amdgcn_s_barrier(); asm volatile("" ::: "memory");
.LBB0_329:
	s_and_saveexec_b64 s[62:63], s[6:7]
	s_cbranch_execz .LBB0_331
	s_waitcnt vmcnt(8)
	v_mov_b32_e32 v70, v65
	v_mov_b32_e32 v71, v66
	v_mov_b32_e32 v65, v67
	v_pk_add_f32 v[64:65], v[70:71], v[64:65]
	s_nop 0
	v_add_f32_e32 v64, v64, v65
	v_fmamk_f32 v64, v64, 0x3a800000, v222
	v_mul_f32_e32 v65, 0x4b800000, v64
	v_cmp_gt_f32_e32 vcc, s45, v64
	s_nop 1
	v_cndmask_b32_e32 v64, v64, v65, vcc
	v_rsq_f32_e32 v64, v64
	s_nop 0
	v_mul_f32_e32 v65, 0x45800000, v64
	v_cndmask_b32_e32 v64, v64, v65, vcc
	ds_write2st64_b32 v155, v64, v68 offset1:4

;     __device__ __forceinline__ Pre prefetch(const Unit& u, int tid) const { return prenorm_load(stats, u.pn * BM, sW + (size_t)(u.pn >> 4) * SW_ROWS + u.pm * BM, tid); }
;     __device__ __forceinline__ Pre prefetch(const Unit& u, int tid) const { return prenorm_load(stats, u.pm * BM, sW + (size_t)(u.pm >> 4) * SW_ROWS + u.pn * BM, tid); }
;     __device__ __forceinline__ Pre prefetch(const Unit& u, int tid) const { return prenorm_load(stats, u.pm * BM, sW + (size_t)(u.pm >> 4) * SW_ROWS + u.pn * BM, tid); }
; #define PG8_STAGE(bufoff, gbase, voff) do { _Pragma("unroll") for (int _i = 0; _i < 2; ++_i) \
;         __builtin_amdgcn_global_load_lds((const unsigned*)((const char*)(gbase) + (voff)[_i]), (LAS unsigned*)(lds + (bufoff) + ldsw + _i * 8192), 16, 0, 0); } while (0)
; #define PG8_WAIT_V(n) asm volatile("s_waitcnt vmcnt(" #n ")" ::: "memory")
; #define PG8_WAIT_L(n) asm volatile("s_waitcnt lgkmcnt(" #n ")" ::: "memory")
;     __device__ __forceinline__ Pre prefetch(const Unit& u, int tid) const {
;         Pre p; p.gv = 0.f; p.gsn = 0.f;
;         if (tid < 256) { const int b = u.pm >> 4, col = u.pn * BM + tid;
;             p.gv = (gate[(size_t)b * NMOD + col] + 1.0f) * coef;
;             if (XT != nullptr) p.gsn = gain_n[col] * (scale_n[(size_t)b * NMOD + col] + 1.0f); }
;         return p;
;     }
; template <class Epi, class Sched>
; __device__ __forceinline__ void gemm_phase(LAS unsigned char* lds, const Gemm g, const Sched& S, const Epi& E, const int tid) {
;     ...
;     for (;;) {
;         const bool has_next = S.next(ui + 1, nxt);
;         const char* nA = has_next ? (const char*)g.A + (size_t)nxt.pm * tstep : cA; const char* nB = has_next ? (const char*)g.Bt + (size_t)nxt.pn * tstep : cB;
;         const typename Epi::Pre pre = E.prefetch(cur, tid);
;         for (int t = 0; t < nt; t += 2) {
;             const bool last = (t == nt - 2);
;             const char* a1 = cA + (size_t)(t + 1) * kstep;
;             const char* a2 = last ? nA : cA + (size_t)(t + 2) * kstep; const char* b2 = last ? nB : cB + (size_t)(t + 2) * kstep;
;             const char* a3 = a2 + kstep; const char* b3 = b2 + kstep;
;             PG8_LDB(B0, 0, 0); PG8_LDB(B1, 0, 1); PG8_SCHED; PG8_LDA(At, 0, 0); PG8_STAGE(PG8_SA(1, 1), a1 + hstep, voffA);
;             PG8_WAIT_V(8); PG8_WAIT_L(0); PG8_BAR; PG8_MMA(0, 0, At, B0); PG8_MMA(0, 1, At, B1); PG8_BAR; PG8_SCHED;
.LBB0_562:
	s_waitcnt lgkmcnt(0)
	v_cndmask_b32_e64 v1, 0, 1, s[48:49]
	v_mov_b32_e32 v0, 0
	v_cmp_ne_u32_e64 s[8:9], 1, v1
	v_mov_b32_e32 v57, 0
	v_mov_b32_e32 v56, 0
	s_and_saveexec_b64 s[82:83], s[10:11]
	s_cbranch_execz .LBB0_566
	v_lshl_add_u32 v2, s66, 8, v229
	s_ashr_i32 s61, s60, 4
	v_ashrrev_i32_e32 v3, 31, v2
	v_mov_b32_e32 v1, 0x2400
	v_mad_i64_i32 v[4:5], vcc, s61, v1, v[2:3]
	v_lshl_add_u64 v[6:7], v[4:5], 2, s[62:63]
	global_load_dword v248, v[6:7], off
	s_and_b64 vcc, exec, s[8:9]
	v_mov_b32_e32 v56, 0
	s_cbranch_vccnz .LBB0_565
	v_lshl_add_u64 v[4:5], v[4:5], 2, s[54:55]
	v_lshl_add_u64 v[2:3], v[2:3], 2, s[50:51]
	global_load_dword v249, v[4:5], off
	s_nop 0
	global_load_dword v250, v[2:3], off
.LBB0_565:
.LBB0_566:
	s_or_b64 exec, exec, s[82:83]
	s_add_u32 vcc_lo, s80, 0x80
	s_addc_u32 vcc_hi, s81, 0
	s_add_u32 s61, s74, 0x100
	s_addc_u32 s67, s75, 0
	s_mov_b32 s74, 0
	s_add_i32 s80, s74, 2
	s_add_u32 s81, vcc_lo, 0x80
	s_addc_u32 s75, vcc_hi, 0
	s_add_i32 s3, 0, 0x10000
	s_cmp_eq_u32 s57, s74
	s_cselect_b32 s75, s71, s75
	s_cselect_b32 s74, s70, s81
	v_add_u32_e32 v70, s3, v232
	s_cselect_b32 s83, s73, s67
	s_cselect_b32 s82, s72, s61
	s_add_i32 s81, 0, 0x14000
	ds_read_b128 v[58:61], v70
	ds_read_b128 v[62:65], v70 offset:1024
	ds_read_b128 v[66:69], v70 offset:2048
	ds_read_b128 v[80:83], v70 offset:3072
	v_add_u32_e32 v70, s81, v232
	ds_read_b128 v[84:87], v70
	ds_read_b128 v[88:91], v70 offset:1024
	ds_read_b128 v[92:95], v70 offset:2048
	ds_read_b128 v[152:155], v70 offset:3072
	v_lshl_add_u64 v[70:71], vcc, 0, v[204:205]
	s_add_i32 m0, s97, 0xc000
	ds_read_b128 v[164:167], v240
	ds_read_b128 v[168:171], v240 offset:1024
	ds_read_b128 v[172:175], v240 offset:2048
	ds_read_b128 v[176:179], v240 offset:3072
	ds_read_b128 v[180:183], v240 offset:4096
	ds_read_b128 v[184:187], v240 offset:5120
	ds_read_b128 v[188:191], v240 offset:6144
	ds_read_b128 v[208:211], v240 offset:7168
	global_load_lds_dwordx4 v[70:71], off
	v_lshl_add_u64 v[70:71], vcc, 0, v[206:207]
	s_add_i32 m0, s97, 0xe000
	s_nop 0
	global_load_lds_dwordx4 v[70:71], off
	s_waitcnt vmcnt(8)
	s_waitcnt lgkmcnt(0)
	s_barrier
	s_setprio 1
	s_waitcnt lgkmcnt(0)
	v_mfma_f32_16x16x32_bf16 v[160:163], v[58:61], v[164:167], 0
	v_mfma_f32_16x16x32_bf16 v[156:159], v[66:69], v[164:167], 0
	v_mfma_f32_16x16x32_bf16 v[140:143], v[58:61], v[172:175], 0
	v_mfma_f32_16x16x32_bf16 v[136:139], v[66:69], v[172:175], 0
	v_mfma_f32_16x16x32_bf16 v[124:127], v[58:61], v[180:183], 0
	v_mfma_f32_16x16x32_bf16 v[120:123], v[66:69], v[180:183], 0
	v_mfma_f32_16x16x32_bf16 v[108:111], v[58:61], v[188:191], 0
	v_mfma_f32_16x16x32_bf16 v[104:107], v[66:69], v[188:191], 0
	v_mfma_f32_16x16x32_bf16 v[160:163], v[62:65], v[168:171], v[160:163]
	v_mfma_f32_16x16x32_bf16 v[156:159], v[80:83], v[168:171], v[156:159]
	v_mfma_f32_16x16x32_bf16 v[140:143], v[62:65], v[176:179], v[140:143]
	v_mfma_f32_16x16x32_bf16 v[136:139], v[80:83], v[176:179], v[136:139]
	v_mfma_f32_16x16x32_bf16 v[124:127], v[62:65], v[184:187], v[124:127]
	v_mfma_f32_16x16x32_bf16 v[120:123], v[80:83], v[184:187], v[120:123]
	v_mfma_f32_16x16x32_bf16 v[108:111], v[62:65], v[208:211], v[108:111]
	v_mfma_f32_16x16x32_bf16 v[104:107], v[80:83], v[208:211], v[104:107]
	s_setprio 0
	s_setprio 1
	v_mfma_f32_16x16x32_bf16 v[148:151], v[84:87], v[164:167], 0
	v_mfma_f32_16x16x32_bf16 v[144:147], v[92:95], v[164:167], 0
	v_mfma_f32_16x16x32_bf16 v[132:135], v[84:87], v[172:175], 0
	v_mfma_f32_16x16x32_bf16 v[128:131], v[92:95], v[172:175], 0
	v_mfma_f32_16x16x32_bf16 v[116:119], v[84:87], v[180:183], 0
	v_mfma_f32_16x16x32_bf16 v[112:115], v[92:95], v[180:183], 0
	v_mfma_f32_16x16x32_bf16 v[100:103], v[84:87], v[188:191], 0
	v_mfma_f32_16x16x32_bf16 v[96:99], v[92:95], v[188:191], 0
	v_mfma_f32_16x16x32_bf16 v[148:151], v[88:91], v[168:171], v[148:151]
	v_mfma_f32_16x16x32_bf16 v[144:147], v[152:155], v[168:171], v[144:147]
	v_mfma_f32_16x16x32_bf16 v[132:135], v[88:91], v[176:179], v[132:135]
	v_mfma_f32_16x16x32_bf16 v[128:131], v[152:155], v[176:179], v[128:131]
	v_mfma_f32_16x16x32_bf16 v[116:119], v[88:91], v[184:187], v[116:119]
	v_mfma_f32_16x16x32_bf16 v[112:115], v[152:155], v[184:187], v[112:115]
	v_mfma_f32_16x16x32_bf16 v[100:103], v[88:91], v[208:211], v[100:103]
	v_mfma_f32_16x16x32_bf16 v[96:99], v[152:155], v[208:211], v[96:99]
	s_setprio 0
	s_barrier
	s_add_i32 s3, s3, s94
	v_lshl_add_u64 v[212:213], s[82:83], 0, v[192:193]
	s_mov_b32 m0, s3
	ds_read_b128 v[164:167], v240 offset:16384
	ds_read_b128 v[168:171], v240 offset:17408
	ds_read_b128 v[172:175], v240 offset:18432
	ds_read_b128 v[176:179], v240 offset:19456
	ds_read_b128 v[180:183], v240 offset:20480
	ds_read_b128 v[184:187], v240 offset:21504
	ds_read_b128 v[188:191], v240 offset:22528
	ds_read_b128 v[208:211], v240 offset:23552
	global_load_lds_dwordx4 v[212:213], off
	s_add_i32 m0, s3, 0x2000
	v_lshl_add_u64 v[214:215], s[82:83], 0, v[198:199]
	s_add_u32 s82, s82, s12
	s_addc_u32 s83, s83, 0
	s_add_i32 s3, s81, s94
	global_load_lds_dwordx4 v[214:215], off
	v_lshl_add_u64 v[216:217], s[82:83], 0, v[192:193]
	s_mov_b32 m0, s3
	v_lshl_add_u64 v[218:219], s[82:83], 0, v[198:199]
	global_load_lds_dwordx4 v[216:217], off
	s_add_i32 m0, s3, 0x2000
	v_lshl_add_u64 v[220:221], s[74:75], 0, v[202:203]
	global_load_lds_dwordx4 v[218:219], off
	s_mov_b32 m0, s97
	v_lshl_add_u64 v[224:225], s[74:75], 0, v[200:201]
	global_load_lds_dwordx4 v[220:221], off
	s_mov_b32 m0, s98
	s_nop 0
	global_load_lds_dwordx4 v[224:225], off
	s_waitcnt vmcnt(8)
	s_waitcnt lgkmcnt(0)
	s_barrier
; #define PG8_STAGE(bufoff, gbase, voff) do { _Pragma("unroll") for (int _i = 0; _i < 2; ++_i) \
;         __builtin_amdgcn_global_load_lds((const unsigned*)((const char*)(gbase) + (voff)[_i]), (LAS unsigned*)(lds + (bufoff) + ldsw + _i * 8192), 16, 0, 0); } while (0)
; #define PG8_LDA(dst, b, h) do { _Pragma("unroll") for (int m = 0; m < 4; ++m) _Pragma("unroll") for (int k = 0; k < 2; ++k) dst[m][k] = *(const LAS bf16x8*)(lds + PG8_SA(b, h) + aoff + m * 2048 + k * 1024); } while (0)
; #define PG8_LDB(dst, b, h) do { _Pragma("unroll") for (int n = 0; n < 2; ++n) _Pragma("unroll") for (int k = 0; k < 2; ++k) dst[n][k] = *(const LAS bf16x8*)(lds + PG8_SB(b, h) + boff + n * 2048 + k * 1024); } while (0)
; #define PG8_MMA(ai, bj, At, Bt) do { __builtin_amdgcn_s_setprio(1); _Pragma("unroll") for (int m = 0; m < 4; ++m) _Pragma("unroll") for (int n = 0; n < 2; ++n) _Pragma("unroll") for (int k = 0; k < 2; ++k) \
;         acc[ai][bj][m][n] = __builtin_amdgcn_mfma_f32_16x16x32_bf16(Bt[n][k], At[m][k], acc[ai][bj][m][n], 0, 0, 0); __builtin_amdgcn_s_setprio(0); } while (0)
; #define PG8_WAIT_V(n) asm volatile("s_waitcnt vmcnt(" #n ")" ::: "memory")
; #define PG8_WAIT_L(n) asm volatile("s_waitcnt lgkmcnt(" #n ")" ::: "memory")
; #define PG8_BAR __builtin_amdgcn_s_barrier()
; #define PG8_SCHED __builtin_amdgcn_sched_barrier(0)
; template <class Epi, class Sched>
; __device__ __forceinline__ void gemm_phase(LAS unsigned char* lds, const Gemm g, const Sched& S, const Epi& E, const int tid) {
;     ...
;             PG8_WAIT_V(8); PG8_WAIT_L(0); PG8_BAR; PG8_MMA(0, 0, At, B0); PG8_MMA(0, 1, At, B1); PG8_BAR; PG8_SCHED;
;             PG8_LDA(At, 0, 1); PG8_STAGE(PG8_SB(0, 0), b2, voffB); PG8_STAGE(PG8_SB(0, 1), b2 + hstep, voffB); PG8_STAGE(PG8_SA(0, 0), a2, voffA);
;             PG8_WAIT_V(8); PG8_WAIT_L(0); PG8_BAR; PG8_MMA(1, 0, At, B0); PG8_MMA(1, 1, At, B1); PG8_BAR; PG8_SCHED;
;             PG8_LDB(B0, 1, 0); PG8_LDB(B1, 1, 1); PG8_SCHED; PG8_LDA(At, 1, 0); PG8_STAGE(PG8_SA(0, 1), a2 + hstep, voffA);
;             PG8_WAIT_V(8); PG8_WAIT_L(0); PG8_BAR; PG8_MMA(0, 0, At, B0); PG8_MMA(0, 1, At, B1); PG8_BAR; PG8_SCHED;
	s_setprio 1
	s_waitcnt lgkmcnt(0)
	v_mfma_f32_16x16x32_bf16 v[76:79], v[58:61], v[164:167], 0
	v_mfma_f32_16x16x32_bf16 v[70:73], v[66:69], v[164:167], 0
	v_mfma_f32_16x16x32_bf16 v[44:47], v[58:61], v[172:175], 0
	v_mfma_f32_16x16x32_bf16 v[40:43], v[66:69], v[172:175], 0
	v_mfma_f32_16x16x32_bf16 v[28:31], v[58:61], v[180:183], 0
	v_mfma_f32_16x16x32_bf16 v[24:27], v[66:69], v[180:183], 0
	v_mfma_f32_16x16x32_bf16 v[12:15], v[58:61], v[188:191], 0
	v_mfma_f32_16x16x32_bf16 v[8:11], v[66:69], v[188:191], 0
	v_mfma_f32_16x16x32_bf16 v[76:79], v[62:65], v[168:171], v[76:79]
	v_mfma_f32_16x16x32_bf16 v[70:73], v[80:83], v[168:171], v[70:73]
	v_mfma_f32_16x16x32_bf16 v[44:47], v[62:65], v[176:179], v[44:47]
	v_mfma_f32_16x16x32_bf16 v[40:43], v[80:83], v[176:179], v[40:43]
	v_mfma_f32_16x16x32_bf16 v[28:31], v[62:65], v[184:187], v[28:31]
	v_mfma_f32_16x16x32_bf16 v[24:27], v[80:83], v[184:187], v[24:27]
	v_mfma_f32_16x16x32_bf16 v[12:15], v[62:65], v[208:211], v[12:15]
	v_mfma_f32_16x16x32_bf16 v[8:11], v[80:83], v[208:211], v[8:11]
	s_setprio 0
	s_setprio 1
	v_mfma_f32_16x16x32_bf16 v[52:55], v[84:87], v[164:167], 0
	v_mfma_f32_16x16x32_bf16 v[48:51], v[92:95], v[164:167], 0
	v_mfma_f32_16x16x32_bf16 v[36:39], v[84:87], v[172:175], 0
	v_mfma_f32_16x16x32_bf16 v[32:35], v[92:95], v[172:175], 0
	v_mfma_f32_16x16x32_bf16 v[20:23], v[84:87], v[180:183], 0
	v_mfma_f32_16x16x32_bf16 v[16:19], v[92:95], v[180:183], 0
	v_mfma_f32_16x16x32_bf16 v[4:7], v[84:87], v[188:191], 0
	v_mfma_f32_16x16x32_bf16 v[0:3], v[92:95], v[188:191], 0
	v_mfma_f32_16x16x32_bf16 v[52:55], v[88:91], v[168:171], v[52:55]
	v_mfma_f32_16x16x32_bf16 v[48:51], v[152:155], v[168:171], v[48:51]
	v_mfma_f32_16x16x32_bf16 v[36:39], v[88:91], v[176:179], v[36:39]
	v_mfma_f32_16x16x32_bf16 v[32:35], v[152:155], v[176:179], v[32:35]
	v_mfma_f32_16x16x32_bf16 v[20:23], v[88:91], v[184:187], v[20:23]
	v_mfma_f32_16x16x32_bf16 v[16:19], v[152:155], v[184:187], v[16:19]
	v_mfma_f32_16x16x32_bf16 v[4:7], v[88:91], v[208:211], v[4:7]
	v_mfma_f32_16x16x32_bf16 v[0:3], v[152:155], v[208:211], v[0:3]
	s_setprio 0
	s_barrier
	s_add_i32 s3, 0, 0x18000
	v_add_u32_e32 v74, s3, v232
	s_add_i32 s81, 0, 0x1c000
	ds_read_b128 v[58:61], v74
	ds_read_b128 v[62:65], v74 offset:1024
	ds_read_b128 v[66:69], v74 offset:2048
	ds_read_b128 v[80:83], v74 offset:3072
	v_add_u32_e32 v74, s81, v232
	ds_read_b128 v[84:87], v74
	ds_read_b128 v[88:91], v74 offset:1024
	ds_read_b128 v[92:95], v74 offset:2048
	ds_read_b128 v[152:155], v74 offset:3072
	s_add_u32 s74, s74, s12
	s_addc_u32 s75, s75, 0
	s_mov_b32 m0, s99
	v_lshl_add_u64 v[74:75], s[74:75], 0, v[202:203]
	ds_read_b128 v[164:167], v240 offset:32768
	ds_read_b128 v[168:171], v240 offset:33792
	ds_read_b128 v[172:175], v240 offset:34816
	ds_read_b128 v[176:179], v240 offset:35840
	ds_read_b128 v[180:183], v240 offset:36864
	ds_read_b128 v[184:187], v240 offset:37888
	ds_read_b128 v[188:191], v240 offset:38912
	ds_read_b128 v[208:211], v240 offset:39936
	global_load_lds_dwordx4 v[74:75], off
	v_lshl_add_u64 v[74:75], s[74:75], 0, v[200:201]
	s_mov_b32 m0, s78
	s_nop 0
	global_load_lds_dwordx4 v[74:75], off
	s_waitcnt vmcnt(8)
	s_waitcnt lgkmcnt(0)
	s_barrier
	s_setprio 1
	s_waitcnt lgkmcnt(0)
	v_mfma_f32_16x16x32_bf16 v[160:163], v[58:61], v[164:167], v[160:163]
	v_mfma_f32_16x16x32_bf16 v[156:159], v[66:69], v[164:167], v[156:159]
	v_mfma_f32_16x16x32_bf16 v[140:143], v[58:61], v[172:175], v[140:143]
	v_mfma_f32_16x16x32_bf16 v[136:139], v[66:69], v[172:175], v[136:139]
	v_mfma_f32_16x16x32_bf16 v[124:127], v[58:61], v[180:183], v[124:127]
	v_mfma_f32_16x16x32_bf16 v[120:123], v[66:69], v[180:183], v[120:123]
	v_mfma_f32_16x16x32_bf16 v[108:111], v[58:61], v[188:191], v[108:111]
	v_mfma_f32_16x16x32_bf16 v[104:107], v[66:69], v[188:191], v[104:107]
	v_mfma_f32_16x16x32_bf16 v[160:163], v[62:65], v[168:171], v[160:163]
	v_mfma_f32_16x16x32_bf16 v[156:159], v[80:83], v[168:171], v[156:159]
	v_mfma_f32_16x16x32_bf16 v[140:143], v[62:65], v[176:179], v[140:143]
	v_mfma_f32_16x16x32_bf16 v[136:139], v[80:83], v[176:179], v[136:139]
	v_mfma_f32_16x16x32_bf16 v[124:127], v[62:65], v[184:187], v[124:127]
	v_mfma_f32_16x16x32_bf16 v[120:123], v[80:83], v[184:187], v[120:123]
	v_mfma_f32_16x16x32_bf16 v[108:111], v[62:65], v[208:211], v[108:111]
	v_mfma_f32_16x16x32_bf16 v[104:107], v[80:83], v[208:211], v[104:107]
	s_setprio 0
	s_setprio 1
	v_mfma_f32_16x16x32_bf16 v[148:151], v[84:87], v[164:167], v[148:151]
	v_mfma_f32_16x16x32_bf16 v[144:147], v[92:95], v[164:167], v[144:147]
	v_mfma_f32_16x16x32_bf16 v[132:135], v[84:87], v[172:175], v[132:135]
	v_mfma_f32_16x16x32_bf16 v[128:131], v[92:95], v[172:175], v[128:131]
	v_mfma_f32_16x16x32_bf16 v[116:119], v[84:87], v[180:183], v[116:119]
	v_mfma_f32_16x16x32_bf16 v[112:115], v[92:95], v[180:183], v[112:115]
	v_mfma_f32_16x16x32_bf16 v[100:103], v[84:87], v[188:191], v[100:103]
	v_mfma_f32_16x16x32_bf16 v[96:99], v[92:95], v[188:191], v[96:99]
	v_mfma_f32_16x16x32_bf16 v[148:151], v[88:91], v[168:171], v[148:151]
	v_mfma_f32_16x16x32_bf16 v[144:147], v[152:155], v[168:171], v[144:147]
	v_mfma_f32_16x16x32_bf16 v[132:135], v[88:91], v[176:179], v[132:135]
	v_mfma_f32_16x16x32_bf16 v[128:131], v[152:155], v[176:179], v[128:131]
	v_mfma_f32_16x16x32_bf16 v[116:119], v[88:91], v[184:187], v[116:119]
	v_mfma_f32_16x16x32_bf16 v[112:115], v[152:155], v[184:187], v[112:115]
	v_mfma_f32_16x16x32_bf16 v[100:103], v[88:91], v[208:211], v[100:103]
	v_mfma_f32_16x16x32_bf16 v[96:99], v[152:155], v[208:211], v[96:99]
	s_setprio 0
	s_barrier
; #define PG8_STAGE(bufoff, gbase, voff) do { _Pragma("unroll") for (int _i = 0; _i < 2; ++_i) \
;         __builtin_amdgcn_global_load_lds((const unsigned*)((const char*)(gbase) + (voff)[_i]), (LAS unsigned*)(lds + (bufoff) + ldsw + _i * 8192), 16, 0, 0); } while (0)
; #define PG8_LDA(dst, b, h) do { _Pragma("unroll") for (int m = 0; m < 4; ++m) _Pragma("unroll") for (int k = 0; k < 2; ++k) dst[m][k] = *(const LAS bf16x8*)(lds + PG8_SA(b, h) + aoff + m * 2048 + k * 1024); } while (0)
; #define PG8_MMA(ai, bj, At, Bt) do { __builtin_amdgcn_s_setprio(1); _Pragma("unroll") for (int m = 0; m < 4; ++m) _Pragma("unroll") for (int n = 0; n < 2; ++n) _Pragma("unroll") for (int k = 0; k < 2; ++k) \
;         acc[ai][bj][m][n] = __builtin_amdgcn_mfma_f32_16x16x32_bf16(Bt[n][k], At[m][k], acc[ai][bj][m][n], 0, 0, 0); __builtin_amdgcn_s_setprio(0); } while (0)
; #define PG8_WAIT_V(n) asm volatile("s_waitcnt vmcnt(" #n ")" ::: "memory")
; #define PG8_WAIT_L(n) asm volatile("s_waitcnt lgkmcnt(" #n ")" ::: "memory")
; #define PG8_BAR __builtin_amdgcn_s_barrier()
; #define PG8_SCHED __builtin_amdgcn_sched_barrier(0)
; template <class Epi, class Sched>
; __device__ __forceinline__ void gemm_phase(LAS unsigned char* lds, const Gemm g, const Sched& S, const Epi& E, const int tid) {
;     ...
;             PG8_WAIT_V(8); PG8_WAIT_L(0); PG8_BAR; PG8_MMA(0, 0, At, B0); PG8_MMA(0, 1, At, B1); PG8_BAR; PG8_SCHED;
;             PG8_LDA(At, 1, 1); PG8_STAGE(PG8_SB(1, 0), b3, voffB); PG8_STAGE(PG8_SB(1, 1), b3 + hstep, voffB); PG8_STAGE(PG8_SA(1, 0), a3, voffA);
;             PG8_WAIT_V(8); PG8_WAIT_L(0); PG8_BAR; PG8_MMA(1, 0, At, B0); PG8_MMA(1, 1, At, B1); PG8_BAR; PG8_SCHED;
;         }
	s_add_i32 s3, s3, s94
	v_lshl_add_u64 v[74:75], v[212:213], 0, s[68:69]
	s_mov_b32 m0, s3
	ds_read_b128 v[164:167], v240 offset:49152
	ds_read_b128 v[168:171], v240 offset:50176
	ds_read_b128 v[172:175], v240 offset:51200
	ds_read_b128 v[176:179], v240 offset:52224
	ds_read_b128 v[180:183], v240 offset:53248
	ds_read_b128 v[184:187], v240 offset:54272
	ds_read_b128 v[188:191], v240 offset:55296
	ds_read_b128 v[208:211], v240 offset:56320
	global_load_lds_dwordx4 v[74:75], off
	v_lshl_add_u64 v[74:75], v[214:215], 0, s[68:69]
	s_add_i32 m0, s3, 0x2000
	s_add_i32 s3, s81, s94
	global_load_lds_dwordx4 v[74:75], off
	v_lshl_add_u64 v[74:75], v[216:217], 0, s[68:69]
	s_mov_b32 m0, s3
	s_nop 0
	global_load_lds_dwordx4 v[74:75], off
	v_lshl_add_u64 v[74:75], v[218:219], 0, s[68:69]
	s_add_i32 m0, s3, 0x2000
	s_nop 0
	global_load_lds_dwordx4 v[74:75], off
	v_lshl_add_u64 v[74:75], v[220:221], 0, s[68:69]
	s_mov_b32 m0, s53
	s_nop 0
	global_load_lds_dwordx4 v[74:75], off
	v_lshl_add_u64 v[74:75], v[224:225], 0, s[68:69]
	s_mov_b32 m0, s56
	s_nop 0
	global_load_lds_dwordx4 v[74:75], off
	s_waitcnt vmcnt(8)
	s_waitcnt lgkmcnt(0)
	s_barrier
	s_setprio 1
	s_waitcnt lgkmcnt(0)
	v_mfma_f32_16x16x32_bf16 v[74:77], v[58:61], v[164:167], v[76:79]
	v_mfma_f32_16x16x32_bf16 v[70:73], v[66:69], v[164:167], v[70:73]
	v_mfma_f32_16x16x32_bf16 v[44:47], v[58:61], v[172:175], v[44:47]
	v_mfma_f32_16x16x32_bf16 v[40:43], v[66:69], v[172:175], v[40:43]
	v_mfma_f32_16x16x32_bf16 v[28:31], v[58:61], v[180:183], v[28:31]
	v_mfma_f32_16x16x32_bf16 v[24:27], v[66:69], v[180:183], v[24:27]
	v_mfma_f32_16x16x32_bf16 v[12:15], v[58:61], v[188:191], v[12:15]
	v_mfma_f32_16x16x32_bf16 v[8:11], v[66:69], v[188:191], v[8:11]
	v_mfma_f32_16x16x32_bf16 v[76:79], v[62:65], v[168:171], v[74:77]
	v_mfma_f32_16x16x32_bf16 v[72:75], v[80:83], v[168:171], v[70:73]
	v_mfma_f32_16x16x32_bf16 v[44:47], v[62:65], v[176:179], v[44:47]
	v_mfma_f32_16x16x32_bf16 v[40:43], v[80:83], v[176:179], v[40:43]
	v_mfma_f32_16x16x32_bf16 v[28:31], v[62:65], v[184:187], v[28:31]
	v_mfma_f32_16x16x32_bf16 v[24:27], v[80:83], v[184:187], v[24:27]
	v_mfma_f32_16x16x32_bf16 v[12:15], v[62:65], v[208:211], v[12:15]
	v_mfma_f32_16x16x32_bf16 v[8:11], v[80:83], v[208:211], v[8:11]
	s_setprio 0
	s_setprio 1
	v_mfma_f32_16x16x32_bf16 v[52:55], v[84:87], v[164:167], v[52:55]
	v_mfma_f32_16x16x32_bf16 v[48:51], v[92:95], v[164:167], v[48:51]
	v_mfma_f32_16x16x32_bf16 v[36:39], v[84:87], v[172:175], v[36:39]
	v_mfma_f32_16x16x32_bf16 v[32:35], v[92:95], v[172:175], v[32:35]
	v_mfma_f32_16x16x32_bf16 v[20:23], v[84:87], v[180:183], v[20:23]
	v_mfma_f32_16x16x32_bf16 v[16:19], v[92:95], v[180:183], v[16:19]
	v_mfma_f32_16x16x32_bf16 v[4:7], v[84:87], v[188:191], v[4:7]
	v_mfma_f32_16x16x32_bf16 v[0:3], v[92:95], v[188:191], v[0:3]
	v_mfma_f32_16x16x32_bf16 v[52:55], v[88:91], v[168:171], v[52:55]
	v_mfma_f32_16x16x32_bf16 v[48:51], v[152:155], v[168:171], v[48:51]
	v_mfma_f32_16x16x32_bf16 v[36:39], v[88:91], v[176:179], v[36:39]
	v_mfma_f32_16x16x32_bf16 v[32:35], v[152:155], v[176:179], v[32:35]
	v_mfma_f32_16x16x32_bf16 v[20:23], v[88:91], v[184:187], v[20:23]
	v_mfma_f32_16x16x32_bf16 v[16:19], v[152:155], v[184:187], v[16:19]
	v_mfma_f32_16x16x32_bf16 v[4:7], v[88:91], v[208:211], v[4:7]
	v_mfma_f32_16x16x32_bf16 v[0:3], v[152:155], v[208:211], v[0:3]
	s_setprio 0
	s_barrier
	s_add_u32 vcc_lo, vcc_lo, 0x100
	s_addc_u32 vcc_hi, vcc_hi, 0
	s_add_u32 s61, s61, 0x100
	s_addc_u32 s67, s67, 0
	s_cmp_ge_u32 s80, s52
	s_mov_b32 s74, s80

; #define LAS __attribute__((address_space(3)))
; #define RES_LOAD(q) do { _Pragma("unroll") for (int mm = 0; mm < 2; ++mm) _Pragma("unroll") for (int bj = 0; bj < 2; ++bj) \
;             bw[q][mm][bj] = __builtin_nontemporal_load((const u32x4*)(base + (size_t)(row0 + ((q) >> 1) * HALF + (((q) & 1) * 2 + mm) * 16) * DM + col0 + bj * HALF)); asm volatile("" ::: "memory"); } while (0)
;     __device__ __forceinline__ void operator()(const f32x4 (&acc)[2][2][4][2], const Unit& u, int wr, int wc, int fr, int fq, int tid, const Pre& pre) const {
;         const int row0 = u.pm * BM + wr * 64 + fr; const int col0 = u.pn * BM + wc * 32 + 8 * fq;
;         const bool nx = (XT != nullptr);
;         u32x4 bw[4][2][2];
;     ...
;         RES_LOAD(0);
;         LAS float* tb = scr + 1024;
;         if (tid < 256) { tb[tid] = pre.gv; tb[256 + tid] = pre.gsn; }
;         asm volatile("s_waitcnt lgkmcnt(0)" ::: "memory"); __builtin_amdgcn_s_barrier(); asm volatile("" ::: "memory");
;         f32x4 gv[2][2], gsn[2][2];
; #pragma unroll
;         for (int bj = 0; bj < 2; ++bj)
; #pragma unroll
;             for (int n = 0; n < 2; ++n) { gv[bj][n] = *(const LAS f32x4*)(tb + bj * HALF + wc * 32 + 8 * fq + 4 * n); gsn[bj][n] = *(const LAS f32x4*)(tb + 256 + bj * HALF + wc * 32 + 8 * fq + 4 * n); }
;         RES_LOAD(1);
; #pragma unroll
;         for (int q = 0; q < 4; ++q) {
;             const int ai = q >> 1;
; #pragma unroll
;             for (int mm = 0; mm < 2; ++mm) { const int m = (q & 1) * 2 + mm; const size_t off = (size_t)(row0 + ai * HALF + m * 16) * DM + col0; float ss = 0.f;
.LBB0_570:
	s_lshl_b32 s60, s60, 8
	v_add_u32_e32 v212, s60, v231
	v_lshl_or_b32 v210, s66, 8, v239
	v_ashrrev_i32_e32 v211, 31, v210
	v_ashrrev_i32_e32 v213, 31, v212
	v_lshl_add_u64 v[208:209], v[210:211], 1, s[42:43]
	v_lshlrev_b64 v[58:59], 11, v[212:213]
	v_or_b32_e32 v218, 16, v212
	v_lshl_add_u64 v[58:59], v[208:209], 0, v[58:59]
	v_ashrrev_i32_e32 v219, 31, v218
	global_load_dwordx4 v[188:191], v[58:59], off nt
	global_load_dwordx4 v[184:187], v[58:59], off offset:256 nt
	v_lshlrev_b64 v[58:59], 11, v[218:219]
	v_lshl_add_u64 v[58:59], v[208:209], 0, v[58:59]
	global_load_dwordx4 v[180:183], v[58:59], off nt
	global_load_dwordx4 v[176:179], v[58:59], off offset:256 nt
	s_and_saveexec_b64 s[74:75], s[10:11]
	s_waitcnt vmcnt(12)
	v_add_f32_e32 v57, 1.0, v248
	v_mov_b32_e32 v56, 0
	s_and_b64 vcc, exec, s[8:9]
	v_mul_f32_e32 v57, s92, v57
	s_cbranch_vccnz .Lres_pre_done
	v_add_f32_e32 v56, 1.0, v249
	s_nop 0
	v_mul_f32_e32 v56, v250, v56
.Lres_pre_done:
	ds_write2st64_b32 v233, v57, v56 offset1:4
	s_or_b64 exec, exec, s[74:75]
	v_or_b32_e32 v216, 32, v212
	v_ashrrev_i32_e32 v217, 31, v216
	v_lshlrev_b64 v[56:57], 11, v[216:217]
	v_or_b32_e32 v214, 48, v212
	s_waitcnt lgkmcnt(0)
	s_barrier
	v_lshl_add_u64 v[56:57], v[208:209], 0, v[56:57]
	v_ashrrev_i32_e32 v215, 31, v214
	global_load_dwordx4 v[172:175], v[56:57], off nt
	global_load_dwordx4 v[168:171], v[56:57], off offset:256 nt
	v_lshlrev_b64 v[56:57], 11, v[214:215]
	v_lshl_add_u64 v[56:57], v[208:209], 0, v[56:57]
	global_load_dwordx4 v[164:167], v[56:57], off nt
	global_load_dwordx4 v[152:155], v[56:57], off offset:256 nt
	s_waitcnt vmcnt(0)
	v_cvt_f32_f16_sdwa v227, v188 dst_sel:DWORD dst_unused:UNUSED_PAD src0_sel:WORD_1
	v_cvt_f32_f16_e32 v226, v188
	v_cvt_f32_f16_sdwa v243, v189 dst_sel:DWORD dst_unused:UNUSED_PAD src0_sel:WORD_1
	v_cvt_f32_f16_e32 v242, v189
	v_cvt_f32_f16_sdwa v189, v190 dst_sel:DWORD dst_unused:UNUSED_PAD src0_sel:WORD_1
	v_cvt_f32_f16_sdwa v245, v191 dst_sel:DWORD dst_unused:UNUSED_PAD src0_sel:WORD_1
	v_cvt_f32_f16_e32 v244, v191
	v_cvt_f32_f16_e32 v188, v190
	ds_read_b128 v[92:95], v234
	ds_read_b128 v[88:91], v234 offset:16
	ds_read_b128 v[84:87], v235
	ds_read_b128 v[80:83], v235 offset:16
	ds_read_b128 v[68:71], v234 offset:512
	ds_read_b128 v[64:67], v234 offset:528
	ds_read_b128 v[60:63], v235 offset:512
	ds_read_b128 v[56:59], v235 offset:528
	v_lshlrev_b64 v[224:225], 10, v[212:213]
	v_lshl_add_u64 v[220:221], v[224:225], 0, v[210:211]
	s_waitcnt lgkmcnt(7)
	v_pk_fma_f32 v[162:163], v[162:163], v[94:95], v[242:243]
	v_pk_fma_f32 v[160:161], v[160:161], v[92:93], v[226:227]
	s_waitcnt lgkmcnt(6)
	v_pk_fma_f32 v[158:159], v[158:159], v[90:91], v[244:245]
	v_pk_fma_f32 v[156:157], v[156:157], v[88:89], v[188:189]
	s_mov_b64 s[74:75], -1
	s_and_b64 vcc, exec, s[8:9]
	v_lshl_add_u64 v[190:191], v[224:225], 1, v[208:209]
	v_lshl_add_u64 v[188:189], v[220:221], 1, s[46:47]
	s_cbranch_vccnz .LBB0_574
	v_mov_b32_e32 v226, v161
	v_mov_b32_e32 v227, v157
	v_mov_b32_e32 v224, v160
	v_mov_b32_e32 v225, v156
	v_pk_mul_f32 v[226:227], v[226:227], v[226:227]
	v_mov_b32_e32 v242, v163
	v_mov_b32_e32 v243, v159
	v_pk_fma_f32 v[224:225], v[224:225], v[224:225], v[226:227]
	v_mov_b32_e32 v226, v162
	v_mov_b32_e32 v227, v158
	v_pk_mul_f32 v[242:243], v[242:243], v[242:243]
	v_cvt_pk_f16_f32 v244, v156, v157
	v_pk_fma_f32 v[226:227], v[226:227], v[226:227], v[242:243]
	v_cvt_pk_f16_f32 v242, v160, v161
	v_pk_add_f32 v[224:225], v[224:225], v[226:227]
	v_cvt_pk_f16_f32 v243, v162, v163
	v_cvt_pk_f16_f32 v245, v158, v159
	v_add_f32_e32 v213, v224, v225
	global_store_dwordx4 v[190:191], v[242:245], off nt
	s_waitcnt lgkmcnt(5)
	v_pk_mul_f32 v[224:225], v[86:87], v[162:163]
	v_pk_mul_f32 v[226:227], v[84:85], v[160:161]
	s_waitcnt lgkmcnt(4)
	v_pk_mul_f32 v[246:247], v[82:83], v[158:159]
	v_pk_mul_f32 v[244:245], v[80:81], v[156:157]
	v_cvt_pk_bf16_f32 v242, v226, v227
	v_cvt_pk_bf16_f32 v243, v224, v225
	v_cvt_pk_bf16_f32 v244, v244, v245
	v_cvt_pk_bf16_f32 v245, v246, v247
	s_mov_b64 s[74:75], 0
	global_store_dwordx4 v[188:189], v[242:245], off
